# baseline (speedup 1.0000x reference)
; #define LDA(dst, b, h) for (int m = 0; m < 4; ++m) for (int k = 0; k < 2; ++k) \
;     dst[m][k] = *reinterpret_cast<const bf16x8*>((char*)SA(b, h) + lds_byte(wr * 64 + m * 16 + fr, k * 32 + fq * 8))
; #define LDB(dst, b, h) for (int n = 0; n < 2; ++n) for (int k = 0; k < 2; ++k) \
;     dst[n][k] = *reinterpret_cast<const bf16x8*>((char*)SB(b, h) + lds_byte(wc * 32 + n * 16 + fr, k * 32 + fq * 8))
; #define MMA(ai, bj, At, Bt_) do { __builtin_amdgcn_s_setprio(1); \
;     for (int m = 0; m < 4; ++m) for (int n = 0; n < 2; ++n) for (int k = 0; k < 2; ++k) \
;       acc[ai][bj][m][n] = __builtin_amdgcn_mfma_f32_16x16x32_bf16(At[m][k], Bt_[n][k], acc[ai][bj][m][n], 0, 0, 0); \
;     __builtin_amdgcn_s_setprio(0); } while (0)
; #define WAIT_L(n) asm volatile("s_waitcnt lgkmcnt(" #n ")" ::: "memory")
; #define BAR __builtin_amdgcn_s_barrier()
; #define SCHED __builtin_amdgcn_sched_barrier(0)
;     ...
;       LDB(B0, 0, 0); SCHED; LDA(At, 0, 0); STAGE(SA(1, 1), A, brow + HALF, t + 1);
;       WAIT_L(8); BAR; WAIT_L(0); MMA(0, 0, At, B0); BAR; SCHED;
;       LDB(B1, 0, 1); STAGE(SB(0, 0), Bt, bcol, t + 2);
;       BAR; WAIT_L(0); MMA(0, 1, At, B1); BAR;
;       LDA(At, 0, 1); STAGE(SA(0, 0), A, brow, t + 2);
;       BAR; WAIT_L(0); MMA(1, 0, At, B0); BAR; SCHED;
.LBB0_98:
	v_add_u32_e32 v143, s2, v142
	ds_read_b128 v[146:149], v143
	ds_read_b128 v[150:153], v143 offset:1024
	ds_read_b128 v[154:157], v143 offset:2048
	ds_read_b128 v[158:161], v143 offset:3072
	s_add_u32 s66, s55, s4
	s_addc_u32 s67, s57, s5
	s_add_i32 s63, s15, 0xc000
	ds_read_b128 v[162:165], v133
	ds_read_b128 v[184:187], v133 offset:1024
	ds_read_b128 v[188:191], v134
	ds_read_b128 v[192:195], v134 offset:1024
	ds_read_b128 v[196:199], v137
	ds_read_b128 v[200:203], v137 offset:1024
	ds_read_b128 v[204:207], v139
	ds_read_b128 v[208:211], v139 offset:1024
	s_mov_b32 m0, s63
	v_lshl_add_u64 v[144:145], s[66:67], 0, v[0:1]
	s_add_i32 s59, s15, 0xe000
	global_load_lds_dwordx4 v[144:145], off
	v_lshl_add_u64 v[144:145], s[66:67], 0, v[140:141]
	s_mov_b32 m0, s59
	s_nop 0
	global_load_lds_dwordx4 v[144:145], off
	s_waitcnt lgkmcnt(8)
	s_barrier
	s_waitcnt lgkmcnt(0)
	s_waitcnt lgkmcnt(0)
	v_mfma_f32_16x16x32_bf16 v[126:129], v[162:165], v[146:149], v[126:129]
	v_mfma_f32_16x16x32_bf16 v[122:125], v[162:165], v[154:157], v[122:125]
	v_mfma_f32_16x16x32_bf16 v[118:121], v[188:191], v[146:149], v[118:121]
	v_mfma_f32_16x16x32_bf16 v[114:117], v[188:191], v[154:157], v[114:117]
	v_mfma_f32_16x16x32_bf16 v[110:113], v[196:199], v[146:149], v[110:113]
	v_mfma_f32_16x16x32_bf16 v[106:109], v[196:199], v[154:157], v[106:109]
	v_mfma_f32_16x16x32_bf16 v[102:105], v[204:207], v[146:149], v[102:105]
	v_mfma_f32_16x16x32_bf16 v[98:101], v[204:207], v[154:157], v[98:101]
	v_mfma_f32_16x16x32_bf16 v[126:129], v[184:187], v[150:153], v[126:129]
	v_mfma_f32_16x16x32_bf16 v[122:125], v[184:187], v[158:161], v[122:125]
	v_mfma_f32_16x16x32_bf16 v[118:121], v[192:195], v[150:153], v[118:121]
	v_mfma_f32_16x16x32_bf16 v[114:117], v[192:195], v[158:161], v[114:117]
	v_mfma_f32_16x16x32_bf16 v[110:113], v[200:203], v[150:153], v[110:113]
	v_mfma_f32_16x16x32_bf16 v[106:109], v[200:203], v[158:161], v[106:109]
	v_mfma_f32_16x16x32_bf16 v[102:105], v[208:211], v[150:153], v[102:105]
	v_mfma_f32_16x16x32_bf16 v[98:101], v[208:211], v[158:161], v[98:101]
	s_barrier
	s_add_i32 s58, s58, 2
	s_add_u32 s65, s50, s4
	s_addc_u32 s70, s51, s5
	s_add_u32 s66, s65, 0x100
	v_add_u32_e32 v144, s76, v142
	s_addc_u32 s67, s70, 0
	s_mov_b32 m0, s16
	ds_read_b128 v[212:215], v144
	ds_read_b128 v[216:219], v144 offset:1024
	ds_read_b128 v[220:223], v144 offset:2048
	ds_read_b128 v[224:227], v144 offset:3072
	v_lshl_add_u64 v[166:167], s[66:67], 0, v[0:1]
	global_load_lds_dwordx4 v[166:167], off
	v_lshl_add_u64 v[166:167], s[66:67], 0, v[140:141]
	s_mov_b32 m0, s17
	s_nop 0
	global_load_lds_dwordx4 v[166:167], off
	s_barrier
	s_waitcnt lgkmcnt(0)
	s_waitcnt lgkmcnt(0)
	v_mfma_f32_16x16x32_bf16 v[94:97], v[162:165], v[212:215], v[94:97]
	v_mfma_f32_16x16x32_bf16 v[90:93], v[162:165], v[220:223], v[90:93]
	v_mfma_f32_16x16x32_bf16 v[86:89], v[188:191], v[212:215], v[86:89]
	v_mfma_f32_16x16x32_bf16 v[82:85], v[188:191], v[220:223], v[82:85]
	v_mfma_f32_16x16x32_bf16 v[78:81], v[196:199], v[212:215], v[78:81]
	v_mfma_f32_16x16x32_bf16 v[74:77], v[196:199], v[220:223], v[74:77]
	v_mfma_f32_16x16x32_bf16 v[70:73], v[204:207], v[212:215], v[70:73]
	v_mfma_f32_16x16x32_bf16 v[66:69], v[204:207], v[220:223], v[66:69]
	v_mfma_f32_16x16x32_bf16 v[94:97], v[184:187], v[216:219], v[94:97]
	v_mfma_f32_16x16x32_bf16 v[90:93], v[184:187], v[224:227], v[90:93]
	v_mfma_f32_16x16x32_bf16 v[86:89], v[192:195], v[216:219], v[86:89]
	v_mfma_f32_16x16x32_bf16 v[82:85], v[192:195], v[224:227], v[82:85]
	v_mfma_f32_16x16x32_bf16 v[78:81], v[200:203], v[216:219], v[78:81]
	v_mfma_f32_16x16x32_bf16 v[74:77], v[200:203], v[224:227], v[74:77]
	v_mfma_f32_16x16x32_bf16 v[70:73], v[208:211], v[216:219], v[70:73]
	v_mfma_f32_16x16x32_bf16 v[66:69], v[208:211], v[224:227], v[66:69]
	s_barrier
	s_add_u32 s71, s44, s4
	s_addc_u32 s72, s45, s5
	s_add_u32 s66, s71, 0x100
	s_addc_u32 s67, s72, 0
	s_mov_b32 m0, s15
	ds_read_b128 v[162:165], v133 offset:16384
	ds_read_b128 v[184:187], v133 offset:17408
	ds_read_b128 v[188:191], v134 offset:16384
	ds_read_b128 v[192:195], v134 offset:17408
	ds_read_b128 v[196:199], v137 offset:16384
	ds_read_b128 v[200:203], v137 offset:17408
	ds_read_b128 v[204:207], v139 offset:16384
	ds_read_b128 v[208:211], v139 offset:17408
	v_lshl_add_u64 v[166:167], s[66:67], 0, v[0:1]
	global_load_lds_dwordx4 v[166:167], off
	v_lshl_add_u64 v[166:167], s[66:67], 0, v[140:141]
	s_mov_b32 m0, s18
	s_nop 0
	global_load_lds_dwordx4 v[166:167], off
	s_barrier
	s_waitcnt lgkmcnt(0)
	s_waitcnt lgkmcnt(0)
	v_mfma_f32_16x16x32_bf16 v[62:65], v[162:165], v[146:149], v[62:65]
	v_mfma_f32_16x16x32_bf16 v[58:61], v[162:165], v[154:157], v[58:61]
	v_mfma_f32_16x16x32_bf16 v[54:57], v[188:191], v[146:149], v[54:57]
	v_mfma_f32_16x16x32_bf16 v[50:53], v[188:191], v[154:157], v[50:53]
	v_mfma_f32_16x16x32_bf16 v[46:49], v[196:199], v[146:149], v[46:49]
	v_mfma_f32_16x16x32_bf16 v[42:45], v[196:199], v[154:157], v[42:45]
	v_mfma_f32_16x16x32_bf16 v[38:41], v[204:207], v[146:149], v[38:41]
	v_mfma_f32_16x16x32_bf16 v[34:37], v[204:207], v[154:157], v[34:37]
	v_mfma_f32_16x16x32_bf16 v[62:65], v[184:187], v[150:153], v[62:65]
	v_mfma_f32_16x16x32_bf16 v[58:61], v[184:187], v[158:161], v[58:61]
	v_mfma_f32_16x16x32_bf16 v[54:57], v[192:195], v[150:153], v[54:57]
	v_mfma_f32_16x16x32_bf16 v[50:53], v[192:195], v[158:161], v[50:53]
	v_mfma_f32_16x16x32_bf16 v[46:49], v[200:203], v[150:153], v[46:49]
	v_mfma_f32_16x16x32_bf16 v[42:45], v[200:203], v[158:161], v[42:45]
	v_mfma_f32_16x16x32_bf16 v[38:41], v[208:211], v[150:153], v[38:41]
	v_mfma_f32_16x16x32_bf16 v[34:37], v[208:211], v[158:161], v[34:37]
	s_barrier
; #define LDA(dst, b, h) for (int m = 0; m < 4; ++m) for (int k = 0; k < 2; ++k) \
;     dst[m][k] = *reinterpret_cast<const bf16x8*>((char*)SA(b, h) + lds_byte(wr * 64 + m * 16 + fr, k * 32 + fq * 8))
; #define LDB(dst, b, h) for (int n = 0; n < 2; ++n) for (int k = 0; k < 2; ++k) \
;     dst[n][k] = *reinterpret_cast<const bf16x8*>((char*)SB(b, h) + lds_byte(wc * 32 + n * 16 + fr, k * 32 + fq * 8))
; #define MMA(ai, bj, At, Bt_) do { __builtin_amdgcn_s_setprio(1); \
;     for (int m = 0; m < 4; ++m) for (int n = 0; n < 2; ++n) for (int k = 0; k < 2; ++k) \
;       acc[ai][bj][m][n] = __builtin_amdgcn_mfma_f32_16x16x32_bf16(At[m][k], Bt_[n][k], acc[ai][bj][m][n], 0, 0, 0); \
;     __builtin_amdgcn_s_setprio(0); } while (0)
; #define WAIT_V(n) asm volatile("s_waitcnt vmcnt(" #n ")" ::: "memory")
; #define WAIT_L(n) asm volatile("s_waitcnt lgkmcnt(" #n ")" ::: "memory")
; #define BAR __builtin_amdgcn_s_barrier()
; #define SCHED __builtin_amdgcn_sched_barrier(0)
;     ...
;       STAGE(SB(0, 1), Bt, bcol + HALF, t + 2);
;       WAIT_V(6); BAR; MMA(1, 1, At, B1); BAR;
;       LDB(B0, 1, 0); SCHED; LDA(At, 1, 0); STAGE(SA(0, 1), A, brow + HALF, t + 2);
;       WAIT_L(8); BAR; WAIT_L(0); MMA(0, 0, At, B0); BAR; SCHED;
;       LDB(B1, 1, 1); STAGE(SB(1, 0), Bt, bcol, t + 3);
;       BAR; WAIT_L(0); MMA(0, 1, At, B1); BAR;
;       LDA(At, 1, 1); STAGE(SA(1, 0), A, brow, t + 3);
	s_add_u32 s73, s6, s4
	s_addc_u32 s82, s7, s5
	s_add_u32 s66, s73, 0x160100
	s_addc_u32 s67, s82, 0
	s_mov_b32 m0, s19
	v_lshl_add_u64 v[146:147], s[66:67], 0, v[0:1]
	global_load_lds_dwordx4 v[146:147], off
	v_lshl_add_u64 v[146:147], s[66:67], 0, v[140:141]
	s_mov_b32 m0, s21
	s_nop 0
	global_load_lds_dwordx4 v[146:147], off
	s_waitcnt vmcnt(6)
	s_barrier
	v_mfma_f32_16x16x32_bf16 v[30:33], v[162:165], v[212:215], v[30:33]
	v_mfma_f32_16x16x32_bf16 v[26:29], v[162:165], v[220:223], v[26:29]
	v_mfma_f32_16x16x32_bf16 v[22:25], v[188:191], v[212:215], v[22:25]
	v_mfma_f32_16x16x32_bf16 v[18:21], v[188:191], v[220:223], v[18:21]
	v_mfma_f32_16x16x32_bf16 v[14:17], v[196:199], v[212:215], v[14:17]
	v_mfma_f32_16x16x32_bf16 v[10:13], v[196:199], v[220:223], v[10:13]
	v_mfma_f32_16x16x32_bf16 v[6:9], v[204:207], v[212:215], v[6:9]
	v_mfma_f32_16x16x32_bf16 v[2:5], v[204:207], v[220:223], v[2:5]
	v_mfma_f32_16x16x32_bf16 v[30:33], v[184:187], v[216:219], v[30:33]
	v_mfma_f32_16x16x32_bf16 v[26:29], v[184:187], v[224:227], v[26:29]
	v_mfma_f32_16x16x32_bf16 v[22:25], v[192:195], v[216:219], v[22:25]
	v_mfma_f32_16x16x32_bf16 v[18:21], v[192:195], v[224:227], v[18:21]
	v_mfma_f32_16x16x32_bf16 v[14:17], v[200:203], v[216:219], v[14:17]
	v_mfma_f32_16x16x32_bf16 v[10:13], v[200:203], v[224:227], v[10:13]
	v_mfma_f32_16x16x32_bf16 v[6:9], v[208:211], v[216:219], v[6:9]
	v_mfma_f32_16x16x32_bf16 v[2:5], v[208:211], v[224:227], v[2:5]
	s_barrier
	v_add_u32_e32 v145, s77, v142
	ds_read_b128 v[148:151], v145
	ds_read_b128 v[152:155], v145 offset:1024
	ds_read_b128 v[156:159], v145 offset:2048
	ds_read_b128 v[160:163], v145 offset:3072
	s_add_u32 s66, s71, 0x160100
	s_addc_u32 s67, s72, 0
	s_mov_b32 m0, s30
	ds_read_b128 v[164:167], v133 offset:32768
	ds_read_b128 v[184:187], v133 offset:33792
	ds_read_b128 v[188:191], v134 offset:32768
	ds_read_b128 v[192:195], v134 offset:33792
	ds_read_b128 v[196:199], v137 offset:32768
	ds_read_b128 v[200:203], v137 offset:33792
	ds_read_b128 v[204:207], v139 offset:32768
	ds_read_b128 v[208:211], v139 offset:33792
	v_lshl_add_u64 v[146:147], s[66:67], 0, v[0:1]
	global_load_lds_dwordx4 v[146:147], off
	v_lshl_add_u64 v[146:147], s[66:67], 0, v[140:141]
	s_mov_b32 m0, s31
	s_nop 0
	global_load_lds_dwordx4 v[146:147], off
	s_waitcnt lgkmcnt(8)
	s_barrier
	s_waitcnt lgkmcnt(0)
	s_waitcnt lgkmcnt(0)
	v_mfma_f32_16x16x32_bf16 v[126:129], v[164:167], v[148:151], v[126:129]
	v_mfma_f32_16x16x32_bf16 v[122:125], v[164:167], v[156:159], v[122:125]
	v_mfma_f32_16x16x32_bf16 v[118:121], v[188:191], v[148:151], v[118:121]
	v_mfma_f32_16x16x32_bf16 v[114:117], v[188:191], v[156:159], v[114:117]
	v_mfma_f32_16x16x32_bf16 v[110:113], v[196:199], v[148:151], v[110:113]
	v_mfma_f32_16x16x32_bf16 v[106:109], v[196:199], v[156:159], v[106:109]
	v_mfma_f32_16x16x32_bf16 v[102:105], v[204:207], v[148:151], v[102:105]
	v_mfma_f32_16x16x32_bf16 v[98:101], v[204:207], v[156:159], v[98:101]
	v_mfma_f32_16x16x32_bf16 v[126:129], v[184:187], v[152:155], v[126:129]
	v_mfma_f32_16x16x32_bf16 v[122:125], v[184:187], v[160:163], v[122:125]
	v_mfma_f32_16x16x32_bf16 v[118:121], v[192:195], v[152:155], v[118:121]
	v_mfma_f32_16x16x32_bf16 v[114:117], v[192:195], v[160:163], v[114:117]
	v_mfma_f32_16x16x32_bf16 v[110:113], v[200:203], v[152:155], v[110:113]
	v_mfma_f32_16x16x32_bf16 v[106:109], v[200:203], v[160:163], v[106:109]
	v_mfma_f32_16x16x32_bf16 v[102:105], v[208:211], v[152:155], v[102:105]
	v_mfma_f32_16x16x32_bf16 v[98:101], v[208:211], v[160:163], v[98:101]
	s_barrier
	s_add_u32 s66, s65, 0x180
	v_add_u32_e32 v146, s78, v142
	s_addc_u32 s67, s70, 0
	s_mov_b32 m0, s34
	ds_read_b128 v[212:215], v146
	ds_read_b128 v[216:219], v146 offset:1024
	ds_read_b128 v[220:223], v146 offset:2048
	ds_read_b128 v[224:227], v146 offset:3072
	v_lshl_add_u64 v[228:229], s[66:67], 0, v[0:1]
	global_load_lds_dwordx4 v[228:229], off
	v_lshl_add_u64 v[228:229], s[66:67], 0, v[140:141]
	s_mov_b32 m0, s35
	s_nop 0
	global_load_lds_dwordx4 v[228:229], off
	s_barrier
	s_waitcnt lgkmcnt(0)
	s_waitcnt lgkmcnt(0)
	v_mfma_f32_16x16x32_bf16 v[94:97], v[164:167], v[212:215], v[94:97]
	v_mfma_f32_16x16x32_bf16 v[90:93], v[164:167], v[220:223], v[90:93]
	v_mfma_f32_16x16x32_bf16 v[86:89], v[188:191], v[212:215], v[86:89]
	v_mfma_f32_16x16x32_bf16 v[82:85], v[188:191], v[220:223], v[82:85]
	v_mfma_f32_16x16x32_bf16 v[78:81], v[196:199], v[212:215], v[78:81]
	v_mfma_f32_16x16x32_bf16 v[74:77], v[196:199], v[220:223], v[74:77]
	v_mfma_f32_16x16x32_bf16 v[70:73], v[204:207], v[212:215], v[70:73]
	v_mfma_f32_16x16x32_bf16 v[66:69], v[204:207], v[220:223], v[66:69]
	v_mfma_f32_16x16x32_bf16 v[94:97], v[184:187], v[216:219], v[94:97]
	v_mfma_f32_16x16x32_bf16 v[90:93], v[184:187], v[224:227], v[90:93]
	v_mfma_f32_16x16x32_bf16 v[86:89], v[192:195], v[216:219], v[86:89]
	v_mfma_f32_16x16x32_bf16 v[82:85], v[192:195], v[224:227], v[82:85]
	v_mfma_f32_16x16x32_bf16 v[78:81], v[200:203], v[216:219], v[78:81]
	v_mfma_f32_16x16x32_bf16 v[74:77], v[200:203], v[224:227], v[74:77]
	v_mfma_f32_16x16x32_bf16 v[70:73], v[208:211], v[216:219], v[70:73]
	v_mfma_f32_16x16x32_bf16 v[66:69], v[208:211], v[224:227], v[66:69]
	s_barrier
	s_add_u32 s66, s71, 0x180
	s_addc_u32 s67, s72, 0
	s_mov_b32 m0, s37
	ds_read_b128 v[164:167], v133 offset:49152
	ds_read_b128 v[184:187], v133 offset:50176
	ds_read_b128 v[188:191], v134 offset:49152
	ds_read_b128 v[192:195], v134 offset:50176
	ds_read_b128 v[196:199], v137 offset:49152
	ds_read_b128 v[200:203], v137 offset:50176
	ds_read_b128 v[204:207], v139 offset:49152
	ds_read_b128 v[208:211], v139 offset:50176
	v_lshl_add_u64 v[228:229], s[66:67], 0, v[0:1]
	global_load_lds_dwordx4 v[228:229], off
	v_lshl_add_u64 v[228:229], s[66:67], 0, v[140:141]
	s_mov_b32 m0, s38
	s_nop 0
	global_load_lds_dwordx4 v[228:229], off
	s_barrier
; #define LDA(dst, b, h) for (int m = 0; m < 4; ++m) for (int k = 0; k < 2; ++k) \
;     dst[m][k] = *reinterpret_cast<const bf16x8*>((char*)SA(b, h) + lds_byte(wr * 64 + m * 16 + fr, k * 32 + fq * 8))
; #define LDB(dst, b, h) for (int n = 0; n < 2; ++n) for (int k = 0; k < 2; ++k) \
;     dst[n][k] = *reinterpret_cast<const bf16x8*>((char*)SB(b, h) + lds_byte(wc * 32 + n * 16 + fr, k * 32 + fq * 8))
; #define MMA(ai, bj, At, Bt_) do { __builtin_amdgcn_s_setprio(1); \
;     for (int m = 0; m < 4; ++m) for (int n = 0; n < 2; ++n) for (int k = 0; k < 2; ++k) \
;       acc[ai][bj][m][n] = __builtin_amdgcn_mfma_f32_16x16x32_bf16(At[m][k], Bt_[n][k], acc[ai][bj][m][n], 0, 0, 0); \
;     __builtin_amdgcn_s_setprio(0); } while (0)
; #define WAIT_V(n) asm volatile("s_waitcnt vmcnt(" #n ")" ::: "memory")
; #define WAIT_L(n) asm volatile("s_waitcnt lgkmcnt(" #n ")" ::: "memory")
; #define BAR __builtin_amdgcn_s_barrier()
; #define SCHED __builtin_amdgcn_sched_barrier(0)
;     ...
;       BAR; WAIT_L(0); MMA(1, 0, At, B0); BAR; SCHED;
;       STAGE(SB(1, 1), Bt, bcol + HALF, t + 3);
;       WAIT_V(6); BAR; MMA(1, 1, At, B1); BAR;
;     }
;     { LDB(B0, 0, 0); LDA(At, 0, 0); STAGE(SA(1, 1), A, brow + HALF, nt - 1);
;       BAR; WAIT_L(0); MMA(0, 0, At, B0); BAR;
;       LDB(B1, 0, 1); BAR; WAIT_L(0); MMA(0, 1, At, B1); BAR;
	s_waitcnt lgkmcnt(0)
	s_waitcnt lgkmcnt(0)
	v_mfma_f32_16x16x32_bf16 v[62:65], v[164:167], v[148:151], v[62:65]
	v_mfma_f32_16x16x32_bf16 v[58:61], v[164:167], v[156:159], v[58:61]
	v_mfma_f32_16x16x32_bf16 v[54:57], v[188:191], v[148:151], v[54:57]
	v_mfma_f32_16x16x32_bf16 v[50:53], v[188:191], v[156:159], v[50:53]
	v_mfma_f32_16x16x32_bf16 v[46:49], v[196:199], v[148:151], v[46:49]
	v_mfma_f32_16x16x32_bf16 v[42:45], v[196:199], v[156:159], v[42:45]
	v_mfma_f32_16x16x32_bf16 v[38:41], v[204:207], v[148:151], v[38:41]
	v_mfma_f32_16x16x32_bf16 v[34:37], v[204:207], v[156:159], v[34:37]
	v_mfma_f32_16x16x32_bf16 v[62:65], v[184:187], v[152:155], v[62:65]
	v_mfma_f32_16x16x32_bf16 v[58:61], v[184:187], v[160:163], v[58:61]
	v_mfma_f32_16x16x32_bf16 v[54:57], v[192:195], v[152:155], v[54:57]
	v_mfma_f32_16x16x32_bf16 v[50:53], v[192:195], v[160:163], v[50:53]
	v_mfma_f32_16x16x32_bf16 v[46:49], v[200:203], v[152:155], v[46:49]
	v_mfma_f32_16x16x32_bf16 v[42:45], v[200:203], v[160:163], v[42:45]
	v_mfma_f32_16x16x32_bf16 v[38:41], v[208:211], v[152:155], v[38:41]
	v_mfma_f32_16x16x32_bf16 v[34:37], v[208:211], v[160:163], v[34:37]
	s_barrier
	s_add_u32 s66, s73, 0x160180
	s_addc_u32 s67, s82, 0
	s_mov_b32 m0, s41
	v_lshl_add_u64 v[148:149], s[66:67], 0, v[0:1]
	global_load_lds_dwordx4 v[148:149], off
	v_lshl_add_u64 v[148:149], s[66:67], 0, v[140:141]
	s_mov_b32 m0, s42
	s_nop 0
	global_load_lds_dwordx4 v[148:149], off
	s_add_u32 s6, s6, 0x100
	s_addc_u32 s7, s7, 0
	s_add_u32 s44, s44, 0x100
	s_addc_u32 s45, s45, 0
	s_add_u32 s50, s50, 0x100
	s_addc_u32 s51, s51, 0
	s_add_u32 s55, s55, 0x100
	s_addc_u32 s57, s57, 0
	s_cmp_ge_u32 s58, s43
	s_waitcnt vmcnt(6)
	s_barrier
	v_mfma_f32_16x16x32_bf16 v[30:33], v[164:167], v[212:215], v[30:33]
	v_mfma_f32_16x16x32_bf16 v[26:29], v[164:167], v[220:223], v[26:29]
	v_mfma_f32_16x16x32_bf16 v[22:25], v[188:191], v[212:215], v[22:25]
	v_mfma_f32_16x16x32_bf16 v[18:21], v[188:191], v[220:223], v[18:21]
	v_mfma_f32_16x16x32_bf16 v[14:17], v[196:199], v[212:215], v[14:17]
	v_mfma_f32_16x16x32_bf16 v[10:13], v[196:199], v[220:223], v[10:13]
	v_mfma_f32_16x16x32_bf16 v[6:9], v[204:207], v[212:215], v[6:9]
	v_mfma_f32_16x16x32_bf16 v[2:5], v[204:207], v[220:223], v[2:5]
	v_mfma_f32_16x16x32_bf16 v[30:33], v[184:187], v[216:219], v[30:33]
	v_mfma_f32_16x16x32_bf16 v[26:29], v[184:187], v[224:227], v[26:29]
	v_mfma_f32_16x16x32_bf16 v[22:25], v[192:195], v[216:219], v[22:25]
	v_mfma_f32_16x16x32_bf16 v[18:21], v[192:195], v[224:227], v[18:21]
	v_mfma_f32_16x16x32_bf16 v[14:17], v[200:203], v[216:219], v[14:17]
	v_mfma_f32_16x16x32_bf16 v[10:13], v[200:203], v[224:227], v[10:13]
	v_mfma_f32_16x16x32_bf16 v[6:9], v[208:211], v[216:219], v[6:9]
	v_mfma_f32_16x16x32_bf16 v[2:5], v[208:211], v[224:227], v[2:5]
	s_barrier
	s_cbranch_scc0 .LBB0_98
	s_add_i32 s4, s48, s14
	s_add_i32 s48, s4, -1
	s_lshl_b64 s[4:5], s[48:49], 7
	s_add_u32 s4, s22, s4
	s_addc_u32 s5, s23, s5
	s_add_u32 s4, s4, s40
	s_addc_u32 s5, s5, s39
	s_mov_b32 m0, s63
	ds_read_b128 v[148:151], v143
	ds_read_b128 v[152:155], v143 offset:1024
	ds_read_b128 v[156:159], v143 offset:2048
	ds_read_b128 v[160:163], v143 offset:3072
	ds_read_b128 v[164:167], v133
	ds_read_b128 v[184:187], v133 offset:1024
	ds_read_b128 v[188:191], v134
	ds_read_b128 v[192:195], v134 offset:1024
	ds_read_b128 v[196:199], v137
	ds_read_b128 v[200:203], v137 offset:1024
	ds_read_b128 v[204:207], v139
	ds_read_b128 v[208:211], v139 offset:1024
	s_nop 0
	v_lshl_add_u64 v[142:143], s[4:5], 0, v[0:1]
	global_load_lds_dwordx4 v[142:143], off
	v_lshl_add_u64 v[140:141], s[4:5], 0, v[140:141]
	s_mov_b32 m0, s59
	s_nop 0
	global_load_lds_dwordx4 v[140:141], off
	s_barrier
	s_waitcnt lgkmcnt(0)
	s_setprio 1
	s_waitcnt lgkmcnt(0)
	v_mfma_f32_16x16x32_bf16 v[126:129], v[164:167], v[148:151], v[126:129]
	v_mfma_f32_16x16x32_bf16 v[122:125], v[164:167], v[156:159], v[122:125]
	v_mfma_f32_16x16x32_bf16 v[118:121], v[188:191], v[148:151], v[118:121]
	v_mfma_f32_16x16x32_bf16 v[110:113], v[196:199], v[148:151], v[110:113]
	v_mfma_f32_16x16x32_bf16 v[106:109], v[196:199], v[156:159], v[106:109]
	v_mfma_f32_16x16x32_bf16 v[102:105], v[204:207], v[148:151], v[102:105]
	v_mfma_f32_16x16x32_bf16 v[98:101], v[204:207], v[156:159], v[98:101]
	v_mfma_f32_16x16x32_bf16 v[126:129], v[184:187], v[152:155], v[126:129]
	v_mfma_f32_16x16x32_bf16 v[122:125], v[184:187], v[160:163], v[122:125]
	v_mfma_f32_16x16x32_bf16 v[118:121], v[192:195], v[152:155], v[118:121]
	v_mfma_f32_16x16x32_bf16 v[114:117], v[188:191], v[156:159], v[114:117]
	v_mfma_f32_16x16x32_bf16 v[110:113], v[200:203], v[152:155], v[110:113]
	v_mfma_f32_16x16x32_bf16 v[106:109], v[200:203], v[160:163], v[106:109]
	v_mfma_f32_16x16x32_bf16 v[102:105], v[208:211], v[152:155], v[102:105]
	v_mfma_f32_16x16x32_bf16 v[98:101], v[208:211], v[160:163], v[98:101]
	v_mfma_f32_16x16x32_bf16 v[140:143], v[192:195], v[160:163], v[114:117]
	s_setprio 0
	s_barrier
	s_nop 0
	ds_read_b128 v[114:117], v144
	ds_read_b128 v[212:215], v144 offset:1024
	ds_read_b128 v[216:219], v144 offset:2048
	ds_read_b128 v[220:223], v144 offset:3072
	s_barrier
; #define LDA(dst, b, h) for (int m = 0; m < 4; ++m) for (int k = 0; k < 2; ++k) \
;     dst[m][k] = *reinterpret_cast<const bf16x8*>((char*)SA(b, h) + lds_byte(wr * 64 + m * 16 + fr, k * 32 + fq * 8))
; #define LDB(dst, b, h) for (int n = 0; n < 2; ++n) for (int k = 0; k < 2; ++k) \
;     dst[n][k] = *reinterpret_cast<const bf16x8*>((char*)SB(b, h) + lds_byte(wc * 32 + n * 16 + fr, k * 32 + fq * 8))
; #define MMA(ai, bj, At, Bt_) do { __builtin_amdgcn_s_setprio(1); \
;     for (int m = 0; m < 4; ++m) for (int n = 0; n < 2; ++n) for (int k = 0; k < 2; ++k) \
;       acc[ai][bj][m][n] = __builtin_amdgcn_mfma_f32_16x16x32_bf16(At[m][k], Bt_[n][k], acc[ai][bj][m][n], 0, 0, 0); \
;     __builtin_amdgcn_s_setprio(0); } while (0)
; #define WAIT_V(n) asm volatile("s_waitcnt vmcnt(" #n ")" ::: "memory")
; #define WAIT_L(n) asm volatile("s_waitcnt lgkmcnt(" #n ")" ::: "memory")
; #define BAR __builtin_amdgcn_s_barrier()
;     ...
;       LDB(B1, 0, 1); BAR; WAIT_L(0); MMA(0, 1, At, B1); BAR;
;       LDA(At, 0, 1); WAIT_V(4); BAR; WAIT_L(0); MMA(1, 0, At, B0); MMA(1, 1, At, B1); BAR; }
;     { LDB(B0, 1, 0); LDA(At, 1, 0); WAIT_V(2); BAR; WAIT_L(0); MMA(0, 0, At, B0); BAR;
	s_waitcnt lgkmcnt(0)
	s_setprio 1
	s_waitcnt lgkmcnt(0)
	v_mfma_f32_16x16x32_bf16 v[90:93], v[164:167], v[216:219], v[90:93]
	v_mfma_f32_16x16x32_bf16 v[86:89], v[188:191], v[114:117], v[86:89]
	v_mfma_f32_16x16x32_bf16 v[94:97], v[164:167], v[114:117], v[94:97]
	v_mfma_f32_16x16x32_bf16 v[90:93], v[184:187], v[220:223], v[90:93]
	v_mfma_f32_16x16x32_bf16 v[86:89], v[192:195], v[212:215], v[86:89]
	v_mfma_f32_16x16x32_bf16 v[82:85], v[188:191], v[216:219], v[82:85]
	v_mfma_f32_16x16x32_bf16 v[78:81], v[196:199], v[114:117], v[78:81]
	v_mfma_f32_16x16x32_bf16 v[74:77], v[196:199], v[216:219], v[74:77]
	v_mfma_f32_16x16x32_bf16 v[70:73], v[204:207], v[114:117], v[70:73]
	v_mfma_f32_16x16x32_bf16 v[66:69], v[204:207], v[216:219], v[66:69]
	v_mfma_f32_16x16x32_bf16 v[224:227], v[184:187], v[212:215], v[94:97]
	v_mfma_f32_16x16x32_bf16 v[164:167], v[192:195], v[220:223], v[82:85]
	v_mfma_f32_16x16x32_bf16 v[184:187], v[200:203], v[212:215], v[78:81]
	v_mfma_f32_16x16x32_bf16 v[188:191], v[200:203], v[220:223], v[74:77]
	v_mfma_f32_16x16x32_bf16 v[192:195], v[208:211], v[212:215], v[70:73]
	v_mfma_f32_16x16x32_bf16 v[196:199], v[208:211], v[220:223], v[66:69]
	s_setprio 0
	s_barrier
	s_nop 0
	ds_read_b128 v[66:69], v133 offset:16384
	ds_read_b128 v[70:73], v133 offset:17408
	ds_read_b128 v[74:77], v134 offset:16384
	ds_read_b128 v[78:81], v134 offset:17408
	ds_read_b128 v[82:85], v137 offset:16384
	ds_read_b128 v[94:97], v137 offset:17408
	ds_read_b128 v[200:203], v139 offset:16384
	ds_read_b128 v[204:207], v139 offset:17408
	s_waitcnt vmcnt(4)
	s_barrier
	s_waitcnt lgkmcnt(0)
	s_setprio 1
	s_waitcnt lgkmcnt(0)
	v_mfma_f32_16x16x32_bf16 v[62:65], v[66:69], v[148:151], v[62:65]
	v_mfma_f32_16x16x32_bf16 v[58:61], v[66:69], v[156:159], v[58:61]
	v_mfma_f32_16x16x32_bf16 v[54:57], v[74:77], v[148:151], v[54:57]
	v_mfma_f32_16x16x32_bf16 v[50:53], v[74:77], v[156:159], v[50:53]
	v_mfma_f32_16x16x32_bf16 v[46:49], v[82:85], v[148:151], v[46:49]
	v_mfma_f32_16x16x32_bf16 v[42:45], v[82:85], v[156:159], v[42:45]
	v_mfma_f32_16x16x32_bf16 v[38:41], v[200:203], v[148:151], v[38:41]
	v_mfma_f32_16x16x32_bf16 v[34:37], v[200:203], v[156:159], v[34:37]
	v_mfma_f32_16x16x32_bf16 v[62:65], v[70:73], v[152:155], v[62:65]
	v_mfma_f32_16x16x32_bf16 v[58:61], v[70:73], v[160:163], v[58:61]
	v_mfma_f32_16x16x32_bf16 v[54:57], v[78:81], v[152:155], v[54:57]
	v_mfma_f32_16x16x32_bf16 v[50:53], v[78:81], v[160:163], v[50:53]
	v_mfma_f32_16x16x32_bf16 v[46:49], v[94:97], v[152:155], v[46:49]
	v_mfma_f32_16x16x32_bf16 v[42:45], v[94:97], v[160:163], v[42:45]
	v_mfma_f32_16x16x32_bf16 v[38:41], v[204:207], v[152:155], v[38:41]
	v_mfma_f32_16x16x32_bf16 v[34:37], v[204:207], v[160:163], v[34:37]
	s_setprio 0
	s_setprio 1
	v_mfma_f32_16x16x32_bf16 v[30:33], v[66:69], v[114:117], v[30:33]
	v_mfma_f32_16x16x32_bf16 v[26:29], v[66:69], v[216:219], v[26:29]
	v_mfma_f32_16x16x32_bf16 v[22:25], v[74:77], v[114:117], v[22:25]
	v_mfma_f32_16x16x32_bf16 v[18:21], v[74:77], v[216:219], v[18:21]
	v_mfma_f32_16x16x32_bf16 v[14:17], v[82:85], v[114:117], v[14:17]
	v_mfma_f32_16x16x32_bf16 v[10:13], v[82:85], v[216:219], v[10:13]
	v_mfma_f32_16x16x32_bf16 v[6:9], v[200:203], v[114:117], v[6:9]
	v_mfma_f32_16x16x32_bf16 v[2:5], v[200:203], v[216:219], v[2:5]
	v_mfma_f32_16x16x32_bf16 v[148:151], v[70:73], v[212:215], v[30:33]
	v_mfma_f32_16x16x32_bf16 v[152:155], v[70:73], v[220:223], v[26:29]
	v_mfma_f32_16x16x32_bf16 v[156:159], v[78:81], v[212:215], v[22:25]
	v_mfma_f32_16x16x32_bf16 v[160:163], v[78:81], v[220:223], v[18:21]
	v_mfma_f32_16x16x32_bf16 v[208:211], v[94:97], v[212:215], v[14:17]
	v_mfma_f32_16x16x32_bf16 v[228:231], v[94:97], v[220:223], v[10:13]
	v_mfma_f32_16x16x32_bf16 v[212:215], v[204:207], v[212:215], v[6:9]
	v_mfma_f32_16x16x32_bf16 v[200:203], v[204:207], v[220:223], v[2:5]
	s_setprio 0
	s_barrier
	ds_read_b128 v[14:17], v145
	ds_read_b128 v[30:33], v145 offset:1024
	ds_read_b128 v[204:207], v145 offset:2048
	ds_read_b128 v[216:219], v145 offset:3072
	ds_read_b128 v[2:5], v133 offset:32768
	ds_read_b128 v[6:9], v133 offset:33792
	ds_read_b128 v[10:13], v134 offset:32768
	ds_read_b128 v[18:21], v134 offset:33792
	ds_read_b128 v[22:25], v137 offset:32768
	ds_read_b128 v[26:29], v137 offset:33792
	ds_read_b128 v[220:223], v139 offset:32768
	ds_read_b128 v[232:235], v139 offset:33792
	s_waitcnt vmcnt(2)
	s_barrier
; #define LDA(dst, b, h) for (int m = 0; m < 4; ++m) for (int k = 0; k < 2; ++k) \
;     dst[m][k] = *reinterpret_cast<const bf16x8*>((char*)SA(b, h) + lds_byte(wr * 64 + m * 16 + fr, k * 32 + fq * 8))
; #define LDB(dst, b, h) for (int n = 0; n < 2; ++n) for (int k = 0; k < 2; ++k) \
;     dst[n][k] = *reinterpret_cast<const bf16x8*>((char*)SB(b, h) + lds_byte(wc * 32 + n * 16 + fr, k * 32 + fq * 8))
; #define MMA(ai, bj, At, Bt_) do { __builtin_amdgcn_s_setprio(1); \
;     for (int m = 0; m < 4; ++m) for (int n = 0; n < 2; ++n) for (int k = 0; k < 2; ++k) \
;       acc[ai][bj][m][n] = __builtin_amdgcn_mfma_f32_16x16x32_bf16(At[m][k], Bt_[n][k], acc[ai][bj][m][n], 0, 0, 0); \
;     __builtin_amdgcn_s_setprio(0); } while (0)
; #define WAIT_V(n) asm volatile("s_waitcnt vmcnt(" #n ")" ::: "memory")
; #define WAIT_L(n) asm volatile("s_waitcnt lgkmcnt(" #n ")" ::: "memory")
; #define BAR __builtin_amdgcn_s_barrier()
;     ...
;     { LDB(B0, 1, 0); LDA(At, 1, 0); WAIT_V(2); BAR; WAIT_L(0); MMA(0, 0, At, B0); BAR;
;       LDB(B1, 1, 1); WAIT_V(0); BAR; WAIT_L(0); MMA(0, 1, At, B1); BAR;
;       LDA(At, 1, 1); BAR; WAIT_L(0); MMA(1, 0, At, B0); MMA(1, 1, At, B1); BAR; }
;     if (wr == 0) BAR;
	s_waitcnt lgkmcnt(0)
	s_setprio 1
	s_waitcnt lgkmcnt(0)
	v_mfma_f32_16x16x32_bf16 v[66:69], v[2:5], v[14:17], v[126:129]
	v_mfma_f32_16x16x32_bf16 v[114:117], v[6:9], v[30:33], v[66:69]
	v_mfma_f32_16x16x32_bf16 v[66:69], v[2:5], v[204:207], v[122:125]
	v_mfma_f32_16x16x32_bf16 v[126:129], v[6:9], v[216:219], v[66:69]
	v_mfma_f32_16x16x32_bf16 v[66:69], v[10:13], v[14:17], v[118:121]
	v_mfma_f32_16x16x32_bf16 v[82:85], v[18:21], v[30:33], v[66:69]
	v_mfma_f32_16x16x32_bf16 v[66:69], v[10:13], v[204:207], v[140:143]
	v_mfma_f32_16x16x32_bf16 v[94:97], v[18:21], v[216:219], v[66:69]
	v_mfma_f32_16x16x32_bf16 v[66:69], v[22:25], v[14:17], v[110:113]
	v_mfma_f32_16x16x32_bf16 v[74:77], v[26:29], v[30:33], v[66:69]
	v_mfma_f32_16x16x32_bf16 v[66:69], v[22:25], v[204:207], v[106:109]
	v_mfma_f32_16x16x32_bf16 v[78:81], v[26:29], v[216:219], v[66:69]
	v_mfma_f32_16x16x32_bf16 v[66:69], v[220:223], v[14:17], v[102:105]
	v_mfma_f32_16x16x32_bf16 v[70:73], v[220:223], v[204:207], v[98:101]
	v_mfma_f32_16x16x32_bf16 v[66:69], v[232:235], v[30:33], v[66:69]
	v_mfma_f32_16x16x32_bf16 v[70:73], v[232:235], v[216:219], v[70:73]
	s_setprio 0
	s_barrier
	ds_read_b128 v[140:143], v146
	ds_read_b128 v[236:239], v146 offset:1024
	ds_read_b128 v[240:243], v146 offset:2048
	ds_read_b128 v[144:147], v146 offset:3072
	s_waitcnt vmcnt(0)
	s_barrier
	s_waitcnt lgkmcnt(0)
	s_setprio 1
	s_waitcnt lgkmcnt(0)
	v_mfma_f32_16x16x32_bf16 v[98:101], v[2:5], v[140:143], v[224:227]
	v_mfma_f32_16x16x32_bf16 v[2:5], v[2:5], v[240:243], v[90:93]
	v_mfma_f32_16x16x32_bf16 v[118:121], v[6:9], v[144:147], v[2:5]
	v_mfma_f32_16x16x32_bf16 v[2:5], v[10:13], v[140:143], v[86:89]
	v_mfma_f32_16x16x32_bf16 v[102:105], v[18:21], v[236:239], v[2:5]
	v_mfma_f32_16x16x32_bf16 v[2:5], v[10:13], v[240:243], v[164:167]
	v_mfma_f32_16x16x32_bf16 v[122:125], v[18:21], v[144:147], v[2:5]
	v_mfma_f32_16x16x32_bf16 v[2:5], v[22:25], v[140:143], v[184:187]
	v_mfma_f32_16x16x32_bf16 v[90:93], v[26:29], v[236:239], v[2:5]
	v_mfma_f32_16x16x32_bf16 v[2:5], v[22:25], v[240:243], v[188:191]
	v_mfma_f32_16x16x32_bf16 v[110:113], v[26:29], v[144:147], v[2:5]
	v_mfma_f32_16x16x32_bf16 v[2:5], v[220:223], v[140:143], v[192:195]
	v_mfma_f32_16x16x32_bf16 v[86:89], v[232:235], v[236:239], v[2:5]
	v_mfma_f32_16x16x32_bf16 v[2:5], v[220:223], v[240:243], v[196:199]
	v_mfma_f32_16x16x32_bf16 v[98:101], v[6:9], v[236:239], v[98:101]
	v_mfma_f32_16x16x32_bf16 v[106:109], v[232:235], v[144:147], v[2:5]
	s_setprio 0
	s_barrier
	ds_read_b128 v[164:167], v133 offset:49152
	ds_read_b128 v[184:187], v133 offset:50176
	ds_read_b128 v[188:191], v134 offset:49152
	ds_read_b128 v[192:195], v134 offset:50176
	ds_read_b128 v[196:199], v137 offset:49152
	ds_read_b128 v[220:223], v137 offset:50176
	ds_read_b128 v[224:227], v139 offset:49152
	ds_read_b128 v[232:235], v139 offset:50176
	s_barrier
	s_waitcnt lgkmcnt(0)
	s_setprio 1
	s_waitcnt lgkmcnt(0)
	v_mfma_f32_16x16x32_bf16 v[6:9], v[164:167], v[204:207], v[58:61]
	v_mfma_f32_16x16x32_bf16 v[10:13], v[188:191], v[204:207], v[50:53]
	v_mfma_f32_16x16x32_bf16 v[2:5], v[164:167], v[14:17], v[62:65]
	v_mfma_f32_16x16x32_bf16 v[18:21], v[184:187], v[216:219], v[6:9]
	v_mfma_f32_16x16x32_bf16 v[6:9], v[188:191], v[14:17], v[54:57]
	v_mfma_f32_16x16x32_bf16 v[22:25], v[192:195], v[216:219], v[10:13]
	v_mfma_f32_16x16x32_bf16 v[10:13], v[196:199], v[14:17], v[46:49]
	v_mfma_f32_16x16x32_bf16 v[14:17], v[224:227], v[14:17], v[38:41]
	v_mfma_f32_16x16x32_bf16 v[2:5], v[184:187], v[30:33], v[2:5]
	v_mfma_f32_16x16x32_bf16 v[6:9], v[192:195], v[30:33], v[6:9]
	v_mfma_f32_16x16x32_bf16 v[10:13], v[220:223], v[30:33], v[10:13]
	v_mfma_f32_16x16x32_bf16 v[26:29], v[196:199], v[204:207], v[42:45]
	v_mfma_f32_16x16x32_bf16 v[14:17], v[232:235], v[30:33], v[14:17]
	v_mfma_f32_16x16x32_bf16 v[30:33], v[224:227], v[204:207], v[34:37]
	v_mfma_f32_16x16x32_bf16 v[26:29], v[220:223], v[216:219], v[26:29]
	v_mfma_f32_16x16x32_bf16 v[30:33], v[232:235], v[216:219], v[30:33]
	s_setprio 0
	s_setprio 1
	v_mfma_f32_16x16x32_bf16 v[38:41], v[164:167], v[240:243], v[152:155]
	v_mfma_f32_16x16x32_bf16 v[42:45], v[188:191], v[240:243], v[160:163]
	v_mfma_f32_16x16x32_bf16 v[46:49], v[196:199], v[240:243], v[228:231]
	v_mfma_f32_16x16x32_bf16 v[34:37], v[164:167], v[140:143], v[148:151]
	v_mfma_f32_16x16x32_bf16 v[50:53], v[184:187], v[144:147], v[38:41]
	v_mfma_f32_16x16x32_bf16 v[38:41], v[188:191], v[140:143], v[156:159]
	v_mfma_f32_16x16x32_bf16 v[54:57], v[192:195], v[144:147], v[42:45]
	v_mfma_f32_16x16x32_bf16 v[42:45], v[196:199], v[140:143], v[208:211]
	v_mfma_f32_16x16x32_bf16 v[58:61], v[220:223], v[144:147], v[46:49]
	v_mfma_f32_16x16x32_bf16 v[46:49], v[224:227], v[140:143], v[212:215]
	v_mfma_f32_16x16x32_bf16 v[62:65], v[224:227], v[240:243], v[200:203]
	v_mfma_f32_16x16x32_bf16 v[34:37], v[184:187], v[236:239], v[34:37]
	v_mfma_f32_16x16x32_bf16 v[38:41], v[192:195], v[236:239], v[38:41]
	v_mfma_f32_16x16x32_bf16 v[42:45], v[220:223], v[236:239], v[42:45]
	v_mfma_f32_16x16x32_bf16 v[46:49], v[232:235], v[236:239], v[46:49]
	v_mfma_f32_16x16x32_bf16 v[62:65], v[232:235], v[144:147], v[62:65]
	s_setprio 0
	v_readlane_b32 s4, v245, 33
	v_readlane_b32 s5, v245, 34
	s_and_b64 vcc, exec, s[4:5]
	s_barrier
	s_cbranch_vccz .LBB0_101
	s_barrier

; #define LDA(dst, b, h) for (int m = 0; m < 4; ++m) for (int k = 0; k < 2; ++k) \
;     dst[m][k] = *reinterpret_cast<const bf16x8*>((char*)SA(b, h) + lds_byte(wr * 64 + m * 16 + fr, k * 32 + fq * 8))
; #define LDB(dst, b, h) for (int n = 0; n < 2; ++n) for (int k = 0; k < 2; ++k) \
;     dst[n][k] = *reinterpret_cast<const bf16x8*>((char*)SB(b, h) + lds_byte(wc * 32 + n * 16 + fr, k * 32 + fq * 8))
; #define MMA(ai, bj, At, Bt_) do { __builtin_amdgcn_s_setprio(1); \
;     for (int m = 0; m < 4; ++m) for (int n = 0; n < 2; ++n) for (int k = 0; k < 2; ++k) \
;       acc[ai][bj][m][n] = __builtin_amdgcn_mfma_f32_16x16x32_bf16(At[m][k], Bt_[n][k], acc[ai][bj][m][n], 0, 0, 0); \
;     __builtin_amdgcn_s_setprio(0); } while (0)
; #define WAIT_L(n) asm volatile("s_waitcnt lgkmcnt(" #n ")" ::: "memory")
; #define BAR __builtin_amdgcn_s_barrier()
; #define SCHED __builtin_amdgcn_sched_barrier(0)
;     ...
;       LDB(B0, 0, 0); SCHED; LDA(At, 0, 0); STAGE(SA(1, 1), A, brow + HALF, t + 1);
;       WAIT_L(8); BAR; WAIT_L(0); MMA(0, 0, At, B0); BAR; SCHED;
;       LDB(B1, 0, 1); STAGE(SB(0, 0), Bt, bcol, t + 2);
;       BAR; WAIT_L(0); MMA(0, 1, At, B1); BAR;
;       LDA(At, 0, 1); STAGE(SA(0, 0), A, brow, t + 2);
;       BAR; WAIT_L(0); MMA(1, 0, At, B0); BAR; SCHED;
.LBB0_155:
	v_add_u32_e32 v143, s2, v142
	ds_read_b128 v[146:149], v143
	ds_read_b128 v[150:153], v143 offset:1024
	ds_read_b128 v[154:157], v143 offset:2048
	ds_read_b128 v[158:161], v143 offset:3072
	s_add_u32 s40, s30, s10
	s_addc_u32 s41, s31, s11
	s_add_u32 s42, s40, 0x80080
	s_addc_u32 s43, s41, 0
	s_add_i32 s39, s24, 0xc000
	ds_read_b128 v[162:165], v133
	ds_read_b128 v[184:187], v133 offset:1024
	ds_read_b128 v[188:191], v134
	ds_read_b128 v[192:195], v134 offset:1024
	ds_read_b128 v[196:199], v137
	ds_read_b128 v[200:203], v137 offset:1024
	ds_read_b128 v[204:207], v139
	ds_read_b128 v[208:211], v139 offset:1024
	s_mov_b32 m0, s39
	v_lshl_add_u64 v[144:145], s[42:43], 0, v[0:1]
	s_add_i32 s38, s24, 0xe000
	global_load_lds_dwordx4 v[144:145], off
	v_lshl_add_u64 v[144:145], s[42:43], 0, v[140:141]
	s_mov_b32 m0, s38
	s_nop 0
	global_load_lds_dwordx4 v[144:145], off
	s_waitcnt lgkmcnt(8)
	s_barrier
	s_waitcnt lgkmcnt(0)
	s_waitcnt lgkmcnt(0)
	v_mfma_f32_16x16x32_bf16 v[126:129], v[162:165], v[146:149], v[126:129]
	v_mfma_f32_16x16x32_bf16 v[122:125], v[162:165], v[154:157], v[122:125]
	v_mfma_f32_16x16x32_bf16 v[118:121], v[188:191], v[146:149], v[118:121]
	v_mfma_f32_16x16x32_bf16 v[114:117], v[188:191], v[154:157], v[114:117]
	v_mfma_f32_16x16x32_bf16 v[110:113], v[196:199], v[146:149], v[110:113]
	v_mfma_f32_16x16x32_bf16 v[106:109], v[196:199], v[154:157], v[106:109]
	v_mfma_f32_16x16x32_bf16 v[102:105], v[204:207], v[146:149], v[102:105]
	v_mfma_f32_16x16x32_bf16 v[98:101], v[204:207], v[154:157], v[98:101]
	v_mfma_f32_16x16x32_bf16 v[126:129], v[184:187], v[150:153], v[126:129]
	v_mfma_f32_16x16x32_bf16 v[122:125], v[184:187], v[158:161], v[122:125]
	v_mfma_f32_16x16x32_bf16 v[118:121], v[192:195], v[150:153], v[118:121]
	v_mfma_f32_16x16x32_bf16 v[114:117], v[192:195], v[158:161], v[114:117]
	v_mfma_f32_16x16x32_bf16 v[110:113], v[200:203], v[150:153], v[110:113]
	v_mfma_f32_16x16x32_bf16 v[106:109], v[200:203], v[158:161], v[106:109]
	v_mfma_f32_16x16x32_bf16 v[102:105], v[208:211], v[150:153], v[102:105]
	v_mfma_f32_16x16x32_bf16 v[98:101], v[208:211], v[158:161], v[98:101]
	s_barrier
	s_add_u32 s42, s34, s10
	s_addc_u32 s43, s35, s11
	s_add_u32 s44, s42, 0x100
	v_add_u32_e32 v144, s76, v142
	s_addc_u32 s45, s43, 0
	s_mov_b32 m0, s25
	ds_read_b128 v[212:215], v144
	ds_read_b128 v[216:219], v144 offset:1024
	ds_read_b128 v[220:223], v144 offset:2048
	ds_read_b128 v[224:227], v144 offset:3072
	v_lshl_add_u64 v[166:167], s[44:45], 0, v[0:1]
	global_load_lds_dwordx4 v[166:167], off
	v_lshl_add_u64 v[166:167], s[44:45], 0, v[140:141]
	s_mov_b32 m0, s26
	s_nop 0
	global_load_lds_dwordx4 v[166:167], off
	s_barrier
	s_waitcnt lgkmcnt(0)
	s_waitcnt lgkmcnt(0)
	v_mfma_f32_16x16x32_bf16 v[94:97], v[162:165], v[212:215], v[94:97]
	v_mfma_f32_16x16x32_bf16 v[90:93], v[162:165], v[220:223], v[90:93]
	v_mfma_f32_16x16x32_bf16 v[86:89], v[188:191], v[212:215], v[86:89]
	v_mfma_f32_16x16x32_bf16 v[82:85], v[188:191], v[220:223], v[82:85]
	v_mfma_f32_16x16x32_bf16 v[78:81], v[196:199], v[212:215], v[78:81]
	v_mfma_f32_16x16x32_bf16 v[74:77], v[196:199], v[220:223], v[74:77]
	v_mfma_f32_16x16x32_bf16 v[70:73], v[204:207], v[212:215], v[70:73]
	v_mfma_f32_16x16x32_bf16 v[66:69], v[204:207], v[220:223], v[66:69]
	v_mfma_f32_16x16x32_bf16 v[94:97], v[184:187], v[216:219], v[94:97]
	v_mfma_f32_16x16x32_bf16 v[90:93], v[184:187], v[224:227], v[90:93]
	v_mfma_f32_16x16x32_bf16 v[86:89], v[192:195], v[216:219], v[86:89]
	v_mfma_f32_16x16x32_bf16 v[82:85], v[192:195], v[224:227], v[82:85]
	v_mfma_f32_16x16x32_bf16 v[78:81], v[200:203], v[216:219], v[78:81]
	v_mfma_f32_16x16x32_bf16 v[74:77], v[200:203], v[224:227], v[74:77]
	v_mfma_f32_16x16x32_bf16 v[70:73], v[208:211], v[216:219], v[70:73]
	v_mfma_f32_16x16x32_bf16 v[66:69], v[208:211], v[224:227], v[66:69]
	s_barrier
	s_add_u32 s44, s40, 0x100
	s_addc_u32 s45, s41, 0
	s_mov_b32 m0, s24
	ds_read_b128 v[162:165], v133 offset:16384
	ds_read_b128 v[184:187], v133 offset:17408
	ds_read_b128 v[188:191], v134 offset:16384
	ds_read_b128 v[192:195], v134 offset:17408
	ds_read_b128 v[196:199], v137 offset:16384
	ds_read_b128 v[200:203], v137 offset:17408
	ds_read_b128 v[204:207], v139 offset:16384
	ds_read_b128 v[208:211], v139 offset:17408
	v_lshl_add_u64 v[166:167], s[44:45], 0, v[0:1]
	global_load_lds_dwordx4 v[166:167], off
	v_lshl_add_u64 v[166:167], s[44:45], 0, v[140:141]
	s_mov_b32 m0, s9
	s_nop 0
	global_load_lds_dwordx4 v[166:167], off
	s_barrier
	s_waitcnt lgkmcnt(0)
	s_waitcnt lgkmcnt(0)
	v_mfma_f32_16x16x32_bf16 v[62:65], v[162:165], v[146:149], v[62:65]
	v_mfma_f32_16x16x32_bf16 v[58:61], v[162:165], v[154:157], v[58:61]
	v_mfma_f32_16x16x32_bf16 v[54:57], v[188:191], v[146:149], v[54:57]
	v_mfma_f32_16x16x32_bf16 v[50:53], v[188:191], v[154:157], v[50:53]
	v_mfma_f32_16x16x32_bf16 v[46:49], v[196:199], v[146:149], v[46:49]
	v_mfma_f32_16x16x32_bf16 v[42:45], v[196:199], v[154:157], v[42:45]
	v_mfma_f32_16x16x32_bf16 v[38:41], v[204:207], v[146:149], v[38:41]
	v_mfma_f32_16x16x32_bf16 v[34:37], v[204:207], v[154:157], v[34:37]
	v_mfma_f32_16x16x32_bf16 v[62:65], v[184:187], v[150:153], v[62:65]
	v_mfma_f32_16x16x32_bf16 v[58:61], v[184:187], v[158:161], v[58:61]
	v_mfma_f32_16x16x32_bf16 v[54:57], v[192:195], v[150:153], v[54:57]
	v_mfma_f32_16x16x32_bf16 v[50:53], v[192:195], v[158:161], v[50:53]
	v_mfma_f32_16x16x32_bf16 v[46:49], v[200:203], v[150:153], v[46:49]
	v_mfma_f32_16x16x32_bf16 v[42:45], v[200:203], v[158:161], v[42:45]
	v_mfma_f32_16x16x32_bf16 v[38:41], v[208:211], v[150:153], v[38:41]
	v_mfma_f32_16x16x32_bf16 v[34:37], v[208:211], v[158:161], v[34:37]
	s_barrier
; #define LDA(dst, b, h) for (int m = 0; m < 4; ++m) for (int k = 0; k < 2; ++k) \
;     dst[m][k] = *reinterpret_cast<const bf16x8*>((char*)SA(b, h) + lds_byte(wr * 64 + m * 16 + fr, k * 32 + fq * 8))
; #define LDB(dst, b, h) for (int n = 0; n < 2; ++n) for (int k = 0; k < 2; ++k) \
;     dst[n][k] = *reinterpret_cast<const bf16x8*>((char*)SB(b, h) + lds_byte(wc * 32 + n * 16 + fr, k * 32 + fq * 8))
; #define MMA(ai, bj, At, Bt_) do { __builtin_amdgcn_s_setprio(1); \
;     for (int m = 0; m < 4; ++m) for (int n = 0; n < 2; ++n) for (int k = 0; k < 2; ++k) \
;       acc[ai][bj][m][n] = __builtin_amdgcn_mfma_f32_16x16x32_bf16(At[m][k], Bt_[n][k], acc[ai][bj][m][n], 0, 0, 0); \
;     __builtin_amdgcn_s_setprio(0); } while (0)
; #define WAIT_V(n) asm volatile("s_waitcnt vmcnt(" #n ")" ::: "memory")
; #define WAIT_L(n) asm volatile("s_waitcnt lgkmcnt(" #n ")" ::: "memory")
; #define BAR __builtin_amdgcn_s_barrier()
; #define SCHED __builtin_amdgcn_sched_barrier(0)
;     ...
;       STAGE(SB(0, 1), Bt, bcol + HALF, t + 2);
;       WAIT_V(6); BAR; MMA(1, 1, At, B1); BAR;
;       LDB(B0, 1, 0); SCHED; LDA(At, 1, 0); STAGE(SA(0, 1), A, brow + HALF, t + 2);
;       WAIT_L(8); BAR; WAIT_L(0); MMA(0, 0, At, B0); BAR; SCHED;
;       LDB(B1, 1, 1); STAGE(SB(1, 0), Bt, bcol, t + 3);
;       BAR; WAIT_L(0); MMA(0, 1, At, B1); BAR;
;       LDA(At, 1, 1); STAGE(SA(1, 0), A, brow, t + 3);
	s_add_u32 s44, s42, 0x80100
	s_addc_u32 s45, s43, 0
	s_mov_b32 m0, s27
	v_lshl_add_u64 v[146:147], s[44:45], 0, v[0:1]
	global_load_lds_dwordx4 v[146:147], off
	v_lshl_add_u64 v[146:147], s[44:45], 0, v[140:141]
	s_mov_b32 m0, s28
	s_nop 0
	global_load_lds_dwordx4 v[146:147], off
	s_waitcnt vmcnt(6)
	s_barrier
	v_mfma_f32_16x16x32_bf16 v[30:33], v[162:165], v[212:215], v[30:33]
	v_mfma_f32_16x16x32_bf16 v[26:29], v[162:165], v[220:223], v[26:29]
	v_mfma_f32_16x16x32_bf16 v[22:25], v[188:191], v[212:215], v[22:25]
	v_mfma_f32_16x16x32_bf16 v[18:21], v[188:191], v[220:223], v[18:21]
	v_mfma_f32_16x16x32_bf16 v[14:17], v[196:199], v[212:215], v[14:17]
	v_mfma_f32_16x16x32_bf16 v[10:13], v[196:199], v[220:223], v[10:13]
	v_mfma_f32_16x16x32_bf16 v[6:9], v[204:207], v[212:215], v[6:9]
	v_mfma_f32_16x16x32_bf16 v[2:5], v[204:207], v[220:223], v[2:5]
	v_mfma_f32_16x16x32_bf16 v[30:33], v[184:187], v[216:219], v[30:33]
	v_mfma_f32_16x16x32_bf16 v[26:29], v[184:187], v[224:227], v[26:29]
	v_mfma_f32_16x16x32_bf16 v[22:25], v[192:195], v[216:219], v[22:25]
	v_mfma_f32_16x16x32_bf16 v[18:21], v[192:195], v[224:227], v[18:21]
	v_mfma_f32_16x16x32_bf16 v[14:17], v[200:203], v[216:219], v[14:17]
	v_mfma_f32_16x16x32_bf16 v[10:13], v[200:203], v[224:227], v[10:13]
	v_mfma_f32_16x16x32_bf16 v[6:9], v[208:211], v[216:219], v[6:9]
	v_mfma_f32_16x16x32_bf16 v[2:5], v[208:211], v[224:227], v[2:5]
	s_barrier
	v_add_u32_e32 v145, s77, v142
	ds_read_b128 v[148:151], v145
	ds_read_b128 v[152:155], v145 offset:1024
	ds_read_b128 v[156:159], v145 offset:2048
	ds_read_b128 v[160:163], v145 offset:3072
	s_add_u32 s44, s40, 0x80100
	s_addc_u32 s45, s41, 0
	s_mov_b32 m0, s7
	ds_read_b128 v[164:167], v133 offset:32768
	ds_read_b128 v[184:187], v133 offset:33792
	ds_read_b128 v[188:191], v134 offset:32768
	ds_read_b128 v[192:195], v134 offset:33792
	ds_read_b128 v[196:199], v137 offset:32768
	ds_read_b128 v[200:203], v137 offset:33792
	ds_read_b128 v[204:207], v139 offset:32768
	ds_read_b128 v[208:211], v139 offset:33792
	v_lshl_add_u64 v[146:147], s[44:45], 0, v[0:1]
	global_load_lds_dwordx4 v[146:147], off
	v_lshl_add_u64 v[146:147], s[44:45], 0, v[140:141]
	s_mov_b32 m0, s29
	s_nop 0
	global_load_lds_dwordx4 v[146:147], off
	s_waitcnt lgkmcnt(8)
	s_barrier
	s_waitcnt lgkmcnt(0)
	s_waitcnt lgkmcnt(0)
	v_mfma_f32_16x16x32_bf16 v[126:129], v[164:167], v[148:151], v[126:129]
	v_mfma_f32_16x16x32_bf16 v[122:125], v[164:167], v[156:159], v[122:125]
	v_mfma_f32_16x16x32_bf16 v[118:121], v[188:191], v[148:151], v[118:121]
	v_mfma_f32_16x16x32_bf16 v[114:117], v[188:191], v[156:159], v[114:117]
	v_mfma_f32_16x16x32_bf16 v[110:113], v[196:199], v[148:151], v[110:113]
	v_mfma_f32_16x16x32_bf16 v[106:109], v[196:199], v[156:159], v[106:109]
	v_mfma_f32_16x16x32_bf16 v[102:105], v[204:207], v[148:151], v[102:105]
	v_mfma_f32_16x16x32_bf16 v[98:101], v[204:207], v[156:159], v[98:101]
	v_mfma_f32_16x16x32_bf16 v[126:129], v[184:187], v[152:155], v[126:129]
	v_mfma_f32_16x16x32_bf16 v[122:125], v[184:187], v[160:163], v[122:125]
	v_mfma_f32_16x16x32_bf16 v[118:121], v[192:195], v[152:155], v[118:121]
	v_mfma_f32_16x16x32_bf16 v[114:117], v[192:195], v[160:163], v[114:117]
	v_mfma_f32_16x16x32_bf16 v[110:113], v[200:203], v[152:155], v[110:113]
	v_mfma_f32_16x16x32_bf16 v[106:109], v[200:203], v[160:163], v[106:109]
	v_mfma_f32_16x16x32_bf16 v[102:105], v[208:211], v[152:155], v[102:105]
	v_mfma_f32_16x16x32_bf16 v[98:101], v[208:211], v[160:163], v[98:101]
	s_barrier
	s_add_u32 s44, s42, 0x180
	v_add_u32_e32 v146, s78, v142
	s_addc_u32 s45, s43, 0
	s_mov_b32 m0, s12
	ds_read_b128 v[212:215], v146
	ds_read_b128 v[216:219], v146 offset:1024
	ds_read_b128 v[220:223], v146 offset:2048
	ds_read_b128 v[224:227], v146 offset:3072
	v_lshl_add_u64 v[228:229], s[44:45], 0, v[0:1]
	global_load_lds_dwordx4 v[228:229], off
	v_lshl_add_u64 v[228:229], s[44:45], 0, v[140:141]
	s_mov_b32 m0, s13
	s_nop 0
	global_load_lds_dwordx4 v[228:229], off
	s_barrier
	s_waitcnt lgkmcnt(0)
	s_waitcnt lgkmcnt(0)
	v_mfma_f32_16x16x32_bf16 v[94:97], v[164:167], v[212:215], v[94:97]
	v_mfma_f32_16x16x32_bf16 v[90:93], v[164:167], v[220:223], v[90:93]
	v_mfma_f32_16x16x32_bf16 v[86:89], v[188:191], v[212:215], v[86:89]
	v_mfma_f32_16x16x32_bf16 v[82:85], v[188:191], v[220:223], v[82:85]
	v_mfma_f32_16x16x32_bf16 v[78:81], v[196:199], v[212:215], v[78:81]
	v_mfma_f32_16x16x32_bf16 v[74:77], v[196:199], v[220:223], v[74:77]
	v_mfma_f32_16x16x32_bf16 v[70:73], v[204:207], v[212:215], v[70:73]
	v_mfma_f32_16x16x32_bf16 v[66:69], v[204:207], v[220:223], v[66:69]
	v_mfma_f32_16x16x32_bf16 v[94:97], v[184:187], v[216:219], v[94:97]
	v_mfma_f32_16x16x32_bf16 v[90:93], v[184:187], v[224:227], v[90:93]
	v_mfma_f32_16x16x32_bf16 v[86:89], v[192:195], v[216:219], v[86:89]
	v_mfma_f32_16x16x32_bf16 v[82:85], v[192:195], v[224:227], v[82:85]
	v_mfma_f32_16x16x32_bf16 v[78:81], v[200:203], v[216:219], v[78:81]
	v_mfma_f32_16x16x32_bf16 v[74:77], v[200:203], v[224:227], v[74:77]
	v_mfma_f32_16x16x32_bf16 v[70:73], v[208:211], v[216:219], v[70:73]
	v_mfma_f32_16x16x32_bf16 v[66:69], v[208:211], v[224:227], v[66:69]
	s_barrier
	s_add_u32 s40, s40, 0x180
	s_addc_u32 s41, s41, 0
	s_mov_b32 m0, s14
	ds_read_b128 v[164:167], v133 offset:49152
	ds_read_b128 v[184:187], v133 offset:50176
	ds_read_b128 v[188:191], v134 offset:49152
	ds_read_b128 v[192:195], v134 offset:50176
	ds_read_b128 v[196:199], v137 offset:49152
	ds_read_b128 v[200:203], v137 offset:50176
	ds_read_b128 v[204:207], v139 offset:49152
	ds_read_b128 v[208:211], v139 offset:50176
	v_lshl_add_u64 v[228:229], s[40:41], 0, v[0:1]
	global_load_lds_dwordx4 v[228:229], off
	v_lshl_add_u64 v[228:229], s[40:41], 0, v[140:141]
	s_mov_b32 m0, s15
	s_nop 0
	global_load_lds_dwordx4 v[228:229], off
	s_barrier
; #define LDA(dst, b, h) for (int m = 0; m < 4; ++m) for (int k = 0; k < 2; ++k) \
;     dst[m][k] = *reinterpret_cast<const bf16x8*>((char*)SA(b, h) + lds_byte(wr * 64 + m * 16 + fr, k * 32 + fq * 8))
; #define LDB(dst, b, h) for (int n = 0; n < 2; ++n) for (int k = 0; k < 2; ++k) \
;     dst[n][k] = *reinterpret_cast<const bf16x8*>((char*)SB(b, h) + lds_byte(wc * 32 + n * 16 + fr, k * 32 + fq * 8))
; #define MMA(ai, bj, At, Bt_) do { __builtin_amdgcn_s_setprio(1); \
;     for (int m = 0; m < 4; ++m) for (int n = 0; n < 2; ++n) for (int k = 0; k < 2; ++k) \
;       acc[ai][bj][m][n] = __builtin_amdgcn_mfma_f32_16x16x32_bf16(At[m][k], Bt_[n][k], acc[ai][bj][m][n], 0, 0, 0); \
;     __builtin_amdgcn_s_setprio(0); } while (0)
; #define WAIT_V(n) asm volatile("s_waitcnt vmcnt(" #n ")" ::: "memory")
; #define WAIT_L(n) asm volatile("s_waitcnt lgkmcnt(" #n ")" ::: "memory")
; #define BAR __builtin_amdgcn_s_barrier()
; #define SCHED __builtin_amdgcn_sched_barrier(0)
;     ...
;       BAR; WAIT_L(0); MMA(1, 0, At, B0); BAR; SCHED;
;       STAGE(SB(1, 1), Bt, bcol + HALF, t + 3);
;       WAIT_V(6); BAR; MMA(1, 1, At, B1); BAR;
;     }
;     { LDB(B0, 0, 0); LDA(At, 0, 0); STAGE(SA(1, 1), A, brow + HALF, nt - 1);
;       BAR; WAIT_L(0); MMA(0, 0, At, B0); BAR;
;       LDB(B1, 0, 1); BAR; WAIT_L(0); MMA(0, 1, At, B1); BAR;
	s_waitcnt lgkmcnt(0)
	s_waitcnt lgkmcnt(0)
	v_mfma_f32_16x16x32_bf16 v[62:65], v[164:167], v[148:151], v[62:65]
	v_mfma_f32_16x16x32_bf16 v[58:61], v[164:167], v[156:159], v[58:61]
	v_mfma_f32_16x16x32_bf16 v[54:57], v[188:191], v[148:151], v[54:57]
	v_mfma_f32_16x16x32_bf16 v[50:53], v[188:191], v[156:159], v[50:53]
	v_mfma_f32_16x16x32_bf16 v[46:49], v[196:199], v[148:151], v[46:49]
	v_mfma_f32_16x16x32_bf16 v[42:45], v[196:199], v[156:159], v[42:45]
	v_mfma_f32_16x16x32_bf16 v[38:41], v[204:207], v[148:151], v[38:41]
	v_mfma_f32_16x16x32_bf16 v[34:37], v[204:207], v[156:159], v[34:37]
	v_mfma_f32_16x16x32_bf16 v[62:65], v[184:187], v[152:155], v[62:65]
	v_mfma_f32_16x16x32_bf16 v[58:61], v[184:187], v[160:163], v[58:61]
	v_mfma_f32_16x16x32_bf16 v[54:57], v[192:195], v[152:155], v[54:57]
	v_mfma_f32_16x16x32_bf16 v[50:53], v[192:195], v[160:163], v[50:53]
	v_mfma_f32_16x16x32_bf16 v[46:49], v[200:203], v[152:155], v[46:49]
	v_mfma_f32_16x16x32_bf16 v[42:45], v[200:203], v[160:163], v[42:45]
	v_mfma_f32_16x16x32_bf16 v[38:41], v[208:211], v[152:155], v[38:41]
	v_mfma_f32_16x16x32_bf16 v[34:37], v[208:211], v[160:163], v[34:37]
	s_barrier
	s_add_u32 s40, s42, 0x80180
	s_addc_u32 s41, s43, 0
	s_mov_b32 m0, s16
	v_lshl_add_u64 v[148:149], s[40:41], 0, v[0:1]
	global_load_lds_dwordx4 v[148:149], off
	v_lshl_add_u64 v[148:149], s[40:41], 0, v[140:141]
	s_mov_b32 m0, s17
	s_nop 0
	global_load_lds_dwordx4 v[148:149], off
	s_add_i32 s37, s37, 2
	s_add_u32 s10, s10, 0x100
	s_addc_u32 s11, s11, 0
	s_cmp_gt_u32 s37, 27
	s_waitcnt vmcnt(6)
	s_barrier
	v_mfma_f32_16x16x32_bf16 v[30:33], v[164:167], v[212:215], v[30:33]
	v_mfma_f32_16x16x32_bf16 v[26:29], v[164:167], v[220:223], v[26:29]
	v_mfma_f32_16x16x32_bf16 v[22:25], v[188:191], v[212:215], v[22:25]
	v_mfma_f32_16x16x32_bf16 v[18:21], v[188:191], v[220:223], v[18:21]
	v_mfma_f32_16x16x32_bf16 v[14:17], v[196:199], v[212:215], v[14:17]
	v_mfma_f32_16x16x32_bf16 v[10:13], v[196:199], v[220:223], v[10:13]
	v_mfma_f32_16x16x32_bf16 v[6:9], v[204:207], v[212:215], v[6:9]
	v_mfma_f32_16x16x32_bf16 v[2:5], v[204:207], v[220:223], v[2:5]
	v_mfma_f32_16x16x32_bf16 v[30:33], v[184:187], v[216:219], v[30:33]
	v_mfma_f32_16x16x32_bf16 v[26:29], v[184:187], v[224:227], v[26:29]
	v_mfma_f32_16x16x32_bf16 v[22:25], v[192:195], v[216:219], v[22:25]
	v_mfma_f32_16x16x32_bf16 v[18:21], v[192:195], v[224:227], v[18:21]
	v_mfma_f32_16x16x32_bf16 v[14:17], v[200:203], v[216:219], v[14:17]
	v_mfma_f32_16x16x32_bf16 v[10:13], v[200:203], v[224:227], v[10:13]
	v_mfma_f32_16x16x32_bf16 v[6:9], v[208:211], v[216:219], v[6:9]
	v_mfma_f32_16x16x32_bf16 v[2:5], v[208:211], v[224:227], v[2:5]
	s_barrier
	s_cbranch_scc0 .LBB0_155
	s_add_u32 s4, s4, 0xf80
	s_addc_u32 s5, s5, 0
	s_mov_b32 m0, s39
	ds_read_b128 v[148:151], v143
	ds_read_b128 v[152:155], v143 offset:1024
	ds_read_b128 v[156:159], v143 offset:2048
	ds_read_b128 v[160:163], v143 offset:3072
	ds_read_b128 v[164:167], v133
	ds_read_b128 v[184:187], v133 offset:1024
	ds_read_b128 v[188:191], v134
	ds_read_b128 v[192:195], v134 offset:1024
	ds_read_b128 v[196:199], v137
	ds_read_b128 v[200:203], v137 offset:1024
	ds_read_b128 v[204:207], v139
	ds_read_b128 v[208:211], v139 offset:1024
	s_nop 0
	v_lshl_add_u64 v[142:143], s[4:5], 0, v[0:1]
	global_load_lds_dwordx4 v[142:143], off
	v_lshl_add_u64 v[140:141], s[4:5], 0, v[140:141]
	s_mov_b32 m0, s38
	s_nop 0
	global_load_lds_dwordx4 v[140:141], off
	s_barrier
	s_waitcnt lgkmcnt(0)
	s_setprio 1
	s_waitcnt lgkmcnt(0)
	v_mfma_f32_16x16x32_bf16 v[126:129], v[164:167], v[148:151], v[126:129]
	v_mfma_f32_16x16x32_bf16 v[118:121], v[188:191], v[148:151], v[118:121]
	v_mfma_f32_16x16x32_bf16 v[110:113], v[196:199], v[148:151], v[110:113]
	v_mfma_f32_16x16x32_bf16 v[102:105], v[204:207], v[148:151], v[102:105]
	v_mfma_f32_16x16x32_bf16 v[126:129], v[184:187], v[152:155], v[126:129]
	v_mfma_f32_16x16x32_bf16 v[122:125], v[164:167], v[156:159], v[122:125]
	v_mfma_f32_16x16x32_bf16 v[118:121], v[192:195], v[152:155], v[118:121]
	v_mfma_f32_16x16x32_bf16 v[114:117], v[188:191], v[156:159], v[114:117]
	v_mfma_f32_16x16x32_bf16 v[110:113], v[200:203], v[152:155], v[110:113]
	v_mfma_f32_16x16x32_bf16 v[106:109], v[196:199], v[156:159], v[106:109]
	v_mfma_f32_16x16x32_bf16 v[102:105], v[208:211], v[152:155], v[102:105]
	v_mfma_f32_16x16x32_bf16 v[98:101], v[204:207], v[156:159], v[98:101]
	v_mfma_f32_16x16x32_bf16 v[140:143], v[184:187], v[160:163], v[122:125]
	v_mfma_f32_16x16x32_bf16 v[212:215], v[192:195], v[160:163], v[114:117]
	v_mfma_f32_16x16x32_bf16 v[216:219], v[200:203], v[160:163], v[106:109]
	v_mfma_f32_16x16x32_bf16 v[220:223], v[208:211], v[160:163], v[98:101]
	s_setprio 0
	s_barrier
	s_nop 1
	ds_read_b128 v[98:101], v144
	ds_read_b128 v[106:109], v144 offset:1024
	ds_read_b128 v[114:117], v144 offset:2048
	ds_read_b128 v[122:125], v144 offset:3072
	s_barrier
	s_waitcnt lgkmcnt(0)
	s_setprio 1
	s_waitcnt lgkmcnt(0)
	v_mfma_f32_16x16x32_bf16 v[94:97], v[164:167], v[98:101], v[94:97]
	v_mfma_f32_16x16x32_bf16 v[86:89], v[188:191], v[98:101], v[86:89]
	v_mfma_f32_16x16x32_bf16 v[78:81], v[196:199], v[98:101], v[78:81]
	v_mfma_f32_16x16x32_bf16 v[70:73], v[204:207], v[98:101], v[70:73]
	v_mfma_f32_16x16x32_bf16 v[94:97], v[184:187], v[106:109], v[94:97]
	v_mfma_f32_16x16x32_bf16 v[90:93], v[164:167], v[114:117], v[90:93]
	v_mfma_f32_16x16x32_bf16 v[86:89], v[192:195], v[106:109], v[86:89]
	v_mfma_f32_16x16x32_bf16 v[82:85], v[188:191], v[114:117], v[82:85]
	v_mfma_f32_16x16x32_bf16 v[78:81], v[200:203], v[106:109], v[78:81]
	v_mfma_f32_16x16x32_bf16 v[74:77], v[196:199], v[114:117], v[74:77]
	v_mfma_f32_16x16x32_bf16 v[70:73], v[208:211], v[106:109], v[70:73]
	v_mfma_f32_16x16x32_bf16 v[66:69], v[204:207], v[114:117], v[66:69]
	v_mfma_f32_16x16x32_bf16 v[164:167], v[184:187], v[122:125], v[90:93]
	v_mfma_f32_16x16x32_bf16 v[184:187], v[192:195], v[122:125], v[82:85]
	v_mfma_f32_16x16x32_bf16 v[188:191], v[200:203], v[122:125], v[74:77]
	v_mfma_f32_16x16x32_bf16 v[192:195], v[208:211], v[122:125], v[66:69]
	s_setprio 0
	s_barrier
; #define LDA(dst, b, h) for (int m = 0; m < 4; ++m) for (int k = 0; k < 2; ++k) \
;     dst[m][k] = *reinterpret_cast<const bf16x8*>((char*)SA(b, h) + lds_byte(wr * 64 + m * 16 + fr, k * 32 + fq * 8))
; #define LDB(dst, b, h) for (int n = 0; n < 2; ++n) for (int k = 0; k < 2; ++k) \
;     dst[n][k] = *reinterpret_cast<const bf16x8*>((char*)SB(b, h) + lds_byte(wc * 32 + n * 16 + fr, k * 32 + fq * 8))
; #define MMA(ai, bj, At, Bt_) do { __builtin_amdgcn_s_setprio(1); \
;     for (int m = 0; m < 4; ++m) for (int n = 0; n < 2; ++n) for (int k = 0; k < 2; ++k) \
;       acc[ai][bj][m][n] = __builtin_amdgcn_mfma_f32_16x16x32_bf16(At[m][k], Bt_[n][k], acc[ai][bj][m][n], 0, 0, 0); \
;     __builtin_amdgcn_s_setprio(0); } while (0)
; #define WAIT_V(n) asm volatile("s_waitcnt vmcnt(" #n ")" ::: "memory")
; #define WAIT_L(n) asm volatile("s_waitcnt lgkmcnt(" #n ")" ::: "memory")
; #define BAR __builtin_amdgcn_s_barrier()
;     ...
;       LDA(At, 0, 1); WAIT_V(4); BAR; WAIT_L(0); MMA(1, 0, At, B0); MMA(1, 1, At, B1); BAR; }
;     { LDB(B0, 1, 0); LDA(At, 1, 0); WAIT_V(2); BAR; WAIT_L(0); MMA(0, 0, At, B0); BAR;
	s_nop 1
	ds_read_b128 v[66:69], v133 offset:16384
	ds_read_b128 v[74:77], v133 offset:17408
	ds_read_b128 v[82:85], v134 offset:16384
	ds_read_b128 v[90:93], v134 offset:17408
	ds_read_b128 v[196:199], v137 offset:16384
	ds_read_b128 v[200:203], v137 offset:17408
	ds_read_b128 v[204:207], v139 offset:16384
	ds_read_b128 v[208:211], v139 offset:17408
	s_waitcnt vmcnt(4)
	s_barrier
	s_waitcnt lgkmcnt(0)
	s_setprio 1
	s_waitcnt lgkmcnt(0)
	v_mfma_f32_16x16x32_bf16 v[62:65], v[66:69], v[148:151], v[62:65]
	v_mfma_f32_16x16x32_bf16 v[54:57], v[82:85], v[148:151], v[54:57]
	v_mfma_f32_16x16x32_bf16 v[46:49], v[196:199], v[148:151], v[46:49]
	v_mfma_f32_16x16x32_bf16 v[38:41], v[204:207], v[148:151], v[38:41]
	v_mfma_f32_16x16x32_bf16 v[62:65], v[74:77], v[152:155], v[62:65]
	v_mfma_f32_16x16x32_bf16 v[58:61], v[66:69], v[156:159], v[58:61]
	v_mfma_f32_16x16x32_bf16 v[54:57], v[90:93], v[152:155], v[54:57]
	v_mfma_f32_16x16x32_bf16 v[50:53], v[82:85], v[156:159], v[50:53]
	v_mfma_f32_16x16x32_bf16 v[46:49], v[200:203], v[152:155], v[46:49]
	v_mfma_f32_16x16x32_bf16 v[42:45], v[196:199], v[156:159], v[42:45]
	v_mfma_f32_16x16x32_bf16 v[38:41], v[208:211], v[152:155], v[38:41]
	v_mfma_f32_16x16x32_bf16 v[34:37], v[204:207], v[156:159], v[34:37]
	v_mfma_f32_16x16x32_bf16 v[224:227], v[74:77], v[160:163], v[58:61]
	v_mfma_f32_16x16x32_bf16 v[228:231], v[90:93], v[160:163], v[50:53]
	v_mfma_f32_16x16x32_bf16 v[232:235], v[200:203], v[160:163], v[42:45]
	v_mfma_f32_16x16x32_bf16 v[148:151], v[208:211], v[160:163], v[34:37]
	s_setprio 0
	s_setprio 1
	v_mfma_f32_16x16x32_bf16 v[30:33], v[66:69], v[98:101], v[30:33]
	v_mfma_f32_16x16x32_bf16 v[22:25], v[82:85], v[98:101], v[22:25]
	v_mfma_f32_16x16x32_bf16 v[14:17], v[196:199], v[98:101], v[14:17]
	v_mfma_f32_16x16x32_bf16 v[6:9], v[204:207], v[98:101], v[6:9]
	v_mfma_f32_16x16x32_bf16 v[30:33], v[74:77], v[106:109], v[30:33]
	v_mfma_f32_16x16x32_bf16 v[26:29], v[66:69], v[114:117], v[26:29]
	v_mfma_f32_16x16x32_bf16 v[22:25], v[90:93], v[106:109], v[22:25]
	v_mfma_f32_16x16x32_bf16 v[18:21], v[82:85], v[114:117], v[18:21]
	v_mfma_f32_16x16x32_bf16 v[14:17], v[200:203], v[106:109], v[14:17]
	v_mfma_f32_16x16x32_bf16 v[10:13], v[196:199], v[114:117], v[10:13]
	v_mfma_f32_16x16x32_bf16 v[6:9], v[208:211], v[106:109], v[6:9]
	v_mfma_f32_16x16x32_bf16 v[2:5], v[204:207], v[114:117], v[2:5]
	v_mfma_f32_16x16x32_bf16 v[152:155], v[74:77], v[122:125], v[26:29]
	v_mfma_f32_16x16x32_bf16 v[156:159], v[90:93], v[122:125], v[18:21]
	v_mfma_f32_16x16x32_bf16 v[160:163], v[200:203], v[122:125], v[10:13]
	v_mfma_f32_16x16x32_bf16 v[196:199], v[208:211], v[122:125], v[2:5]
	s_setprio 0
	s_barrier
	s_nop 1
	ds_read_b128 v[2:5], v145
	ds_read_b128 v[10:13], v145 offset:1024
	ds_read_b128 v[200:203], v145 offset:2048
	ds_read_b128 v[204:207], v145 offset:3072
	ds_read_b128 v[18:21], v133 offset:32768
	ds_read_b128 v[26:29], v133 offset:33792
	ds_read_b128 v[34:37], v134 offset:32768
	ds_read_b128 v[42:45], v134 offset:33792
	ds_read_b128 v[50:53], v137 offset:32768
	ds_read_b128 v[58:61], v137 offset:33792
	ds_read_b128 v[208:211], v139 offset:32768
	ds_read_b128 v[236:239], v139 offset:33792
	s_waitcnt vmcnt(2)
	s_barrier
	s_waitcnt lgkmcnt(0)
	s_setprio 1
	s_waitcnt lgkmcnt(0)
	v_mfma_f32_16x16x32_bf16 v[66:69], v[18:21], v[2:5], v[126:129]
	v_mfma_f32_16x16x32_bf16 v[122:125], v[26:29], v[10:13], v[66:69]
	v_mfma_f32_16x16x32_bf16 v[66:69], v[18:21], v[200:203], v[140:143]
	v_mfma_f32_16x16x32_bf16 v[114:117], v[26:29], v[204:207], v[66:69]
	v_mfma_f32_16x16x32_bf16 v[66:69], v[34:37], v[2:5], v[118:121]
	v_mfma_f32_16x16x32_bf16 v[106:109], v[42:45], v[10:13], v[66:69]
	v_mfma_f32_16x16x32_bf16 v[66:69], v[34:37], v[200:203], v[212:215]
	v_mfma_f32_16x16x32_bf16 v[98:101], v[42:45], v[204:207], v[66:69]
	v_mfma_f32_16x16x32_bf16 v[66:69], v[50:53], v[2:5], v[110:113]
	v_mfma_f32_16x16x32_bf16 v[90:93], v[58:61], v[10:13], v[66:69]
	v_mfma_f32_16x16x32_bf16 v[66:69], v[50:53], v[200:203], v[216:219]
	v_mfma_f32_16x16x32_bf16 v[82:85], v[58:61], v[204:207], v[66:69]
	v_mfma_f32_16x16x32_bf16 v[66:69], v[208:211], v[2:5], v[102:105]
	v_mfma_f32_16x16x32_bf16 v[74:77], v[236:239], v[10:13], v[66:69]
	v_mfma_f32_16x16x32_bf16 v[66:69], v[208:211], v[200:203], v[220:223]
	v_mfma_f32_16x16x32_bf16 v[66:69], v[236:239], v[204:207], v[66:69]
	s_setprio 0
	s_barrier
; #define LDA(dst, b, h) for (int m = 0; m < 4; ++m) for (int k = 0; k < 2; ++k) \
;     dst[m][k] = *reinterpret_cast<const bf16x8*>((char*)SA(b, h) + lds_byte(wr * 64 + m * 16 + fr, k * 32 + fq * 8))
; #define LDB(dst, b, h) for (int n = 0; n < 2; ++n) for (int k = 0; k < 2; ++k) \
;     dst[n][k] = *reinterpret_cast<const bf16x8*>((char*)SB(b, h) + lds_byte(wc * 32 + n * 16 + fr, k * 32 + fq * 8))
; #define MMA(ai, bj, At, Bt_) do { __builtin_amdgcn_s_setprio(1); \
;     for (int m = 0; m < 4; ++m) for (int n = 0; n < 2; ++n) for (int k = 0; k < 2; ++k) \
;       acc[ai][bj][m][n] = __builtin_amdgcn_mfma_f32_16x16x32_bf16(At[m][k], Bt_[n][k], acc[ai][bj][m][n], 0, 0, 0); \
;     __builtin_amdgcn_s_setprio(0); } while (0)
; #define WAIT_V(n) asm volatile("s_waitcnt vmcnt(" #n ")" ::: "memory")
; #define WAIT_L(n) asm volatile("s_waitcnt lgkmcnt(" #n ")" ::: "memory")
; #define BAR __builtin_amdgcn_s_barrier()
;     ...
;       LDB(B1, 1, 1); WAIT_V(0); BAR; WAIT_L(0); MMA(0, 1, At, B1); BAR;
;       LDA(At, 1, 1); BAR; WAIT_L(0); MMA(1, 0, At, B0); MMA(1, 1, At, B1); BAR; }
;     if (wr == 0) BAR;
	ds_read_b128 v[140:143], v146
	ds_read_b128 v[212:215], v146 offset:1024
	ds_read_b128 v[216:219], v146 offset:2048
	ds_read_b128 v[144:147], v146 offset:3072
	s_waitcnt vmcnt(0)
	s_barrier
	s_waitcnt lgkmcnt(0)
	s_setprio 1
	s_waitcnt lgkmcnt(0)
	v_mfma_f32_16x16x32_bf16 v[94:97], v[18:21], v[140:143], v[94:97]
	v_mfma_f32_16x16x32_bf16 v[18:21], v[18:21], v[216:219], v[164:167]
	v_mfma_f32_16x16x32_bf16 v[118:121], v[26:29], v[144:147], v[18:21]
	v_mfma_f32_16x16x32_bf16 v[18:21], v[34:37], v[140:143], v[86:89]
	v_mfma_f32_16x16x32_bf16 v[110:113], v[42:45], v[212:215], v[18:21]
	v_mfma_f32_16x16x32_bf16 v[18:21], v[34:37], v[216:219], v[184:187]
	v_mfma_f32_16x16x32_bf16 v[102:105], v[42:45], v[144:147], v[18:21]
	v_mfma_f32_16x16x32_bf16 v[18:21], v[50:53], v[140:143], v[78:81]
	v_mfma_f32_16x16x32_bf16 v[126:129], v[26:29], v[212:215], v[94:97]
	v_mfma_f32_16x16x32_bf16 v[94:97], v[58:61], v[212:215], v[18:21]
	v_mfma_f32_16x16x32_bf16 v[18:21], v[50:53], v[216:219], v[188:191]
	v_mfma_f32_16x16x32_bf16 v[86:89], v[58:61], v[144:147], v[18:21]
	v_mfma_f32_16x16x32_bf16 v[18:21], v[208:211], v[140:143], v[70:73]
	v_mfma_f32_16x16x32_bf16 v[78:81], v[236:239], v[212:215], v[18:21]
	v_mfma_f32_16x16x32_bf16 v[18:21], v[208:211], v[216:219], v[192:195]
	v_mfma_f32_16x16x32_bf16 v[70:73], v[236:239], v[144:147], v[18:21]
	s_setprio 0
	s_barrier
	ds_read_b128 v[164:167], v133 offset:49152
	ds_read_b128 v[184:187], v133 offset:50176
	ds_read_b128 v[188:191], v134 offset:49152
	ds_read_b128 v[192:195], v134 offset:50176
	ds_read_b128 v[208:211], v137 offset:49152
	ds_read_b128 v[220:223], v137 offset:50176
	ds_read_b128 v[236:239], v139 offset:49152
	ds_read_b128 v[240:243], v139 offset:50176
	s_barrier
	s_waitcnt lgkmcnt(0)
	s_setprio 1
	s_waitcnt lgkmcnt(0)
	v_mfma_f32_16x16x32_bf16 v[18:21], v[164:167], v[2:5], v[62:65]
	v_mfma_f32_16x16x32_bf16 v[58:61], v[184:187], v[10:13], v[18:21]
	v_mfma_f32_16x16x32_bf16 v[18:21], v[164:167], v[200:203], v[224:227]
	v_mfma_f32_16x16x32_bf16 v[50:53], v[184:187], v[204:207], v[18:21]
	v_mfma_f32_16x16x32_bf16 v[18:21], v[188:191], v[2:5], v[54:57]
	v_mfma_f32_16x16x32_bf16 v[42:45], v[192:195], v[10:13], v[18:21]
	v_mfma_f32_16x16x32_bf16 v[18:21], v[188:191], v[200:203], v[228:231]
	v_mfma_f32_16x16x32_bf16 v[34:37], v[192:195], v[204:207], v[18:21]
	v_mfma_f32_16x16x32_bf16 v[18:21], v[208:211], v[2:5], v[46:49]
	v_mfma_f32_16x16x32_bf16 v[2:5], v[236:239], v[2:5], v[38:41]
	v_mfma_f32_16x16x32_bf16 v[26:29], v[220:223], v[10:13], v[18:21]
	v_mfma_f32_16x16x32_bf16 v[18:21], v[208:211], v[200:203], v[232:235]
	v_mfma_f32_16x16x32_bf16 v[10:13], v[240:243], v[10:13], v[2:5]
	v_mfma_f32_16x16x32_bf16 v[2:5], v[236:239], v[200:203], v[148:151]
	v_mfma_f32_16x16x32_bf16 v[18:21], v[220:223], v[204:207], v[18:21]
	v_mfma_f32_16x16x32_bf16 v[2:5], v[240:243], v[204:207], v[2:5]
	s_setprio 0
	s_setprio 1
	v_mfma_f32_16x16x32_bf16 v[30:33], v[164:167], v[140:143], v[30:33]
	v_mfma_f32_16x16x32_bf16 v[62:65], v[184:187], v[212:215], v[30:33]
	v_mfma_f32_16x16x32_bf16 v[30:33], v[164:167], v[216:219], v[152:155]
	v_mfma_f32_16x16x32_bf16 v[22:25], v[188:191], v[140:143], v[22:25]
	v_mfma_f32_16x16x32_bf16 v[14:17], v[208:211], v[140:143], v[14:17]
	v_mfma_f32_16x16x32_bf16 v[54:57], v[184:187], v[144:147], v[30:33]
	v_mfma_f32_16x16x32_bf16 v[46:49], v[192:195], v[212:215], v[22:25]
	v_mfma_f32_16x16x32_bf16 v[22:25], v[188:191], v[216:219], v[156:159]
	v_mfma_f32_16x16x32_bf16 v[30:33], v[220:223], v[212:215], v[14:17]
	v_mfma_f32_16x16x32_bf16 v[14:17], v[208:211], v[216:219], v[160:163]
	v_mfma_f32_16x16x32_bf16 v[6:9], v[236:239], v[140:143], v[6:9]
	v_mfma_f32_16x16x32_bf16 v[38:41], v[192:195], v[144:147], v[22:25]
	v_mfma_f32_16x16x32_bf16 v[22:25], v[220:223], v[144:147], v[14:17]
	v_mfma_f32_16x16x32_bf16 v[14:17], v[240:243], v[212:215], v[6:9]
	v_mfma_f32_16x16x32_bf16 v[6:9], v[236:239], v[216:219], v[196:199]
	v_mfma_f32_16x16x32_bf16 v[6:9], v[240:243], v[144:147], v[6:9]
	s_setprio 0
	v_readlane_b32 s4, v245, 33
	v_readlane_b32 s5, v245, 34
	s_and_b64 vcc, exec, s[4:5]
	s_barrier
	s_cbranch_vccz .LBB0_158
	s_barrier

; #define LDA(dst, b, h) for (int m = 0; m < 4; ++m) for (int k = 0; k < 2; ++k) \
;     dst[m][k] = *reinterpret_cast<const bf16x8*>((char*)SA(b, h) + lds_byte(wr * 64 + m * 16 + fr, k * 32 + fq * 8))
; #define LDB(dst, b, h) for (int n = 0; n < 2; ++n) for (int k = 0; k < 2; ++k) \
;     dst[n][k] = *reinterpret_cast<const bf16x8*>((char*)SB(b, h) + lds_byte(wc * 32 + n * 16 + fr, k * 32 + fq * 8))
; #define MMA(ai, bj, At, Bt_) do { __builtin_amdgcn_s_setprio(1); \
;     for (int m = 0; m < 4; ++m) for (int n = 0; n < 2; ++n) for (int k = 0; k < 2; ++k) \
;       acc[ai][bj][m][n] = __builtin_amdgcn_mfma_f32_16x16x32_bf16(At[m][k], Bt_[n][k], acc[ai][bj][m][n], 0, 0, 0); \
;     __builtin_amdgcn_s_setprio(0); } while (0)
; #define WAIT_L(n) asm volatile("s_waitcnt lgkmcnt(" #n ")" ::: "memory")
; #define BAR __builtin_amdgcn_s_barrier()
; #define SCHED __builtin_amdgcn_sched_barrier(0)
;     ...
;       LDB(B0, 0, 0); SCHED; LDA(At, 0, 0); STAGE(SA(1, 1), A, brow + HALF, t + 1);
;       WAIT_L(8); BAR; WAIT_L(0); MMA(0, 0, At, B0); BAR; SCHED;
;       LDB(B1, 0, 1); STAGE(SB(0, 0), Bt, bcol, t + 2);
;       BAR; WAIT_L(0); MMA(0, 1, At, B1); BAR;
;       LDA(At, 0, 1); STAGE(SA(0, 0), A, brow, t + 2);
;       BAR; WAIT_L(0); MMA(1, 0, At, B0); BAR; SCHED;
.LBB0_202:
	v_add_u32_e32 v143, s2, v142
	ds_read_b128 v[146:149], v143
	ds_read_b128 v[150:153], v143 offset:1024
	ds_read_b128 v[154:157], v143 offset:2048
	ds_read_b128 v[158:161], v143 offset:3072
	s_add_u32 s66, s50, s16
	s_addc_u32 s67, s51, s17
	s_add_i32 s58, s21, 0xc000
	ds_read_b128 v[162:165], v133
	ds_read_b128 v[184:187], v133 offset:1024
	ds_read_b128 v[188:191], v134
	ds_read_b128 v[192:195], v134 offset:1024
	ds_read_b128 v[196:199], v137
	ds_read_b128 v[200:203], v137 offset:1024
	ds_read_b128 v[204:207], v139
	ds_read_b128 v[208:211], v139 offset:1024
	s_mov_b32 m0, s58
	v_lshl_add_u64 v[144:145], s[66:67], 0, v[0:1]
	s_add_i32 s57, s21, 0xe000
	global_load_lds_dwordx4 v[144:145], off
	v_lshl_add_u64 v[144:145], s[66:67], 0, v[140:141]
	s_mov_b32 m0, s57
	s_nop 0
	global_load_lds_dwordx4 v[144:145], off
	s_waitcnt lgkmcnt(8)
	s_barrier
	s_waitcnt lgkmcnt(0)
	s_waitcnt lgkmcnt(0)
	v_mfma_f32_16x16x32_bf16 v[126:129], v[162:165], v[146:149], v[126:129]
	v_mfma_f32_16x16x32_bf16 v[122:125], v[162:165], v[154:157], v[122:125]
	v_mfma_f32_16x16x32_bf16 v[118:121], v[188:191], v[146:149], v[118:121]
	v_mfma_f32_16x16x32_bf16 v[114:117], v[188:191], v[154:157], v[114:117]
	v_mfma_f32_16x16x32_bf16 v[110:113], v[196:199], v[146:149], v[110:113]
	v_mfma_f32_16x16x32_bf16 v[106:109], v[196:199], v[154:157], v[106:109]
	v_mfma_f32_16x16x32_bf16 v[102:105], v[204:207], v[146:149], v[102:105]
	v_mfma_f32_16x16x32_bf16 v[98:101], v[204:207], v[154:157], v[98:101]
	v_mfma_f32_16x16x32_bf16 v[126:129], v[184:187], v[150:153], v[126:129]
	v_mfma_f32_16x16x32_bf16 v[122:125], v[184:187], v[158:161], v[122:125]
	v_mfma_f32_16x16x32_bf16 v[118:121], v[192:195], v[150:153], v[118:121]
	v_mfma_f32_16x16x32_bf16 v[114:117], v[192:195], v[158:161], v[114:117]
	v_mfma_f32_16x16x32_bf16 v[110:113], v[200:203], v[150:153], v[110:113]
	v_mfma_f32_16x16x32_bf16 v[106:109], v[200:203], v[158:161], v[106:109]
	v_mfma_f32_16x16x32_bf16 v[102:105], v[208:211], v[150:153], v[102:105]
	v_mfma_f32_16x16x32_bf16 v[98:101], v[208:211], v[158:161], v[98:101]
	s_barrier
	s_add_i32 s55, s55, 2
	s_add_u32 s59, s11, s16
	s_addc_u32 s63, s44, s17
	s_add_u32 s66, s59, 0x100
	v_add_u32_e32 v144, s76, v142
	s_addc_u32 s67, s63, 0
	s_mov_b32 m0, s29
	ds_read_b128 v[212:215], v144
	ds_read_b128 v[216:219], v144 offset:1024
	ds_read_b128 v[220:223], v144 offset:2048
	ds_read_b128 v[224:227], v144 offset:3072
	v_lshl_add_u64 v[166:167], s[66:67], 0, v[0:1]
	global_load_lds_dwordx4 v[166:167], off
	v_lshl_add_u64 v[166:167], s[66:67], 0, v[140:141]
	s_mov_b32 m0, s30
	s_nop 0
	global_load_lds_dwordx4 v[166:167], off
	s_barrier
	s_waitcnt lgkmcnt(0)
	s_waitcnt lgkmcnt(0)
	v_mfma_f32_16x16x32_bf16 v[94:97], v[162:165], v[212:215], v[94:97]
	v_mfma_f32_16x16x32_bf16 v[90:93], v[162:165], v[220:223], v[90:93]
	v_mfma_f32_16x16x32_bf16 v[86:89], v[188:191], v[212:215], v[86:89]
	v_mfma_f32_16x16x32_bf16 v[82:85], v[188:191], v[220:223], v[82:85]
	v_mfma_f32_16x16x32_bf16 v[78:81], v[196:199], v[212:215], v[78:81]
	v_mfma_f32_16x16x32_bf16 v[74:77], v[196:199], v[220:223], v[74:77]
	v_mfma_f32_16x16x32_bf16 v[70:73], v[204:207], v[212:215], v[70:73]
	v_mfma_f32_16x16x32_bf16 v[66:69], v[204:207], v[220:223], v[66:69]
	v_mfma_f32_16x16x32_bf16 v[94:97], v[184:187], v[216:219], v[94:97]
	v_mfma_f32_16x16x32_bf16 v[90:93], v[184:187], v[224:227], v[90:93]
	v_mfma_f32_16x16x32_bf16 v[86:89], v[192:195], v[216:219], v[86:89]
	v_mfma_f32_16x16x32_bf16 v[82:85], v[192:195], v[224:227], v[82:85]
	v_mfma_f32_16x16x32_bf16 v[78:81], v[200:203], v[216:219], v[78:81]
	v_mfma_f32_16x16x32_bf16 v[74:77], v[200:203], v[224:227], v[74:77]
	v_mfma_f32_16x16x32_bf16 v[70:73], v[208:211], v[216:219], v[70:73]
	v_mfma_f32_16x16x32_bf16 v[66:69], v[208:211], v[224:227], v[66:69]
	s_barrier
	s_add_u32 s65, s13, s16
	s_addc_u32 s70, s45, s17
	s_add_u32 s66, s65, 0x100
	s_addc_u32 s67, s70, 0
	s_mov_b32 m0, s21
	ds_read_b128 v[162:165], v133 offset:16384
	ds_read_b128 v[184:187], v133 offset:17408
	ds_read_b128 v[188:191], v134 offset:16384
	ds_read_b128 v[192:195], v134 offset:17408
	ds_read_b128 v[196:199], v137 offset:16384
	ds_read_b128 v[200:203], v137 offset:17408
	ds_read_b128 v[204:207], v139 offset:16384
	ds_read_b128 v[208:211], v139 offset:17408
	v_lshl_add_u64 v[166:167], s[66:67], 0, v[0:1]
	global_load_lds_dwordx4 v[166:167], off
	v_lshl_add_u64 v[166:167], s[66:67], 0, v[140:141]
	s_mov_b32 m0, s31
	s_nop 0
	global_load_lds_dwordx4 v[166:167], off
	s_barrier
	s_waitcnt lgkmcnt(0)
	s_waitcnt lgkmcnt(0)
	v_mfma_f32_16x16x32_bf16 v[62:65], v[162:165], v[146:149], v[62:65]
	v_mfma_f32_16x16x32_bf16 v[58:61], v[162:165], v[154:157], v[58:61]
	v_mfma_f32_16x16x32_bf16 v[54:57], v[188:191], v[146:149], v[54:57]
	v_mfma_f32_16x16x32_bf16 v[50:53], v[188:191], v[154:157], v[50:53]
	v_mfma_f32_16x16x32_bf16 v[46:49], v[196:199], v[146:149], v[46:49]
	v_mfma_f32_16x16x32_bf16 v[42:45], v[196:199], v[154:157], v[42:45]
	v_mfma_f32_16x16x32_bf16 v[38:41], v[204:207], v[146:149], v[38:41]
	v_mfma_f32_16x16x32_bf16 v[34:37], v[204:207], v[154:157], v[34:37]
	v_mfma_f32_16x16x32_bf16 v[62:65], v[184:187], v[150:153], v[62:65]
	v_mfma_f32_16x16x32_bf16 v[58:61], v[184:187], v[158:161], v[58:61]
	v_mfma_f32_16x16x32_bf16 v[54:57], v[192:195], v[150:153], v[54:57]
	v_mfma_f32_16x16x32_bf16 v[50:53], v[192:195], v[158:161], v[50:53]
	v_mfma_f32_16x16x32_bf16 v[46:49], v[200:203], v[150:153], v[46:49]
	v_mfma_f32_16x16x32_bf16 v[42:45], v[200:203], v[158:161], v[42:45]
	v_mfma_f32_16x16x32_bf16 v[38:41], v[208:211], v[150:153], v[38:41]
	v_mfma_f32_16x16x32_bf16 v[34:37], v[208:211], v[158:161], v[34:37]
	s_barrier
; #define LDA(dst, b, h) for (int m = 0; m < 4; ++m) for (int k = 0; k < 2; ++k) \
;     dst[m][k] = *reinterpret_cast<const bf16x8*>((char*)SA(b, h) + lds_byte(wr * 64 + m * 16 + fr, k * 32 + fq * 8))
; #define LDB(dst, b, h) for (int n = 0; n < 2; ++n) for (int k = 0; k < 2; ++k) \
;     dst[n][k] = *reinterpret_cast<const bf16x8*>((char*)SB(b, h) + lds_byte(wc * 32 + n * 16 + fr, k * 32 + fq * 8))
; #define MMA(ai, bj, At, Bt_) do { __builtin_amdgcn_s_setprio(1); \
;     for (int m = 0; m < 4; ++m) for (int n = 0; n < 2; ++n) for (int k = 0; k < 2; ++k) \
;       acc[ai][bj][m][n] = __builtin_amdgcn_mfma_f32_16x16x32_bf16(At[m][k], Bt_[n][k], acc[ai][bj][m][n], 0, 0, 0); \
;     __builtin_amdgcn_s_setprio(0); } while (0)
; #define WAIT_V(n) asm volatile("s_waitcnt vmcnt(" #n ")" ::: "memory")
; #define WAIT_L(n) asm volatile("s_waitcnt lgkmcnt(" #n ")" ::: "memory")
; #define BAR __builtin_amdgcn_s_barrier()
; #define SCHED __builtin_amdgcn_sched_barrier(0)
;     ...
;       STAGE(SB(0, 1), Bt, bcol + HALF, t + 2);
;       WAIT_V(6); BAR; MMA(1, 1, At, B1); BAR;
;       LDB(B0, 1, 0); SCHED; LDA(At, 1, 0); STAGE(SA(0, 1), A, brow + HALF, t + 2);
;       WAIT_L(8); BAR; WAIT_L(0); MMA(0, 0, At, B0); BAR; SCHED;
;       LDB(B1, 1, 1); STAGE(SB(1, 0), Bt, bcol, t + 3);
;       BAR; WAIT_L(0); MMA(0, 1, At, B1); BAR;
;       LDA(At, 1, 1); STAGE(SA(1, 0), A, brow, t + 3);
	s_add_u32 s66, s59, 0x80100
	s_addc_u32 s67, s63, 0
	s_mov_b32 m0, s34
	v_lshl_add_u64 v[146:147], s[66:67], 0, v[0:1]
	global_load_lds_dwordx4 v[146:147], off
	v_lshl_add_u64 v[146:147], s[66:67], 0, v[140:141]
	s_mov_b32 m0, s35
	s_nop 0
	global_load_lds_dwordx4 v[146:147], off
	s_waitcnt vmcnt(6)
	s_barrier
	v_mfma_f32_16x16x32_bf16 v[30:33], v[162:165], v[212:215], v[30:33]
	v_mfma_f32_16x16x32_bf16 v[26:29], v[162:165], v[220:223], v[26:29]
	v_mfma_f32_16x16x32_bf16 v[22:25], v[188:191], v[212:215], v[22:25]
	v_mfma_f32_16x16x32_bf16 v[18:21], v[188:191], v[220:223], v[18:21]
	v_mfma_f32_16x16x32_bf16 v[14:17], v[196:199], v[212:215], v[14:17]
	v_mfma_f32_16x16x32_bf16 v[10:13], v[196:199], v[220:223], v[10:13]
	v_mfma_f32_16x16x32_bf16 v[6:9], v[204:207], v[212:215], v[6:9]
	v_mfma_f32_16x16x32_bf16 v[2:5], v[204:207], v[220:223], v[2:5]
	v_mfma_f32_16x16x32_bf16 v[30:33], v[184:187], v[216:219], v[30:33]
	v_mfma_f32_16x16x32_bf16 v[26:29], v[184:187], v[224:227], v[26:29]
	v_mfma_f32_16x16x32_bf16 v[22:25], v[192:195], v[216:219], v[22:25]
	v_mfma_f32_16x16x32_bf16 v[18:21], v[192:195], v[224:227], v[18:21]
	v_mfma_f32_16x16x32_bf16 v[14:17], v[200:203], v[216:219], v[14:17]
	v_mfma_f32_16x16x32_bf16 v[10:13], v[200:203], v[224:227], v[10:13]
	v_mfma_f32_16x16x32_bf16 v[6:9], v[208:211], v[216:219], v[6:9]
	v_mfma_f32_16x16x32_bf16 v[2:5], v[208:211], v[224:227], v[2:5]
	s_barrier
	v_add_u32_e32 v145, s77, v142
	ds_read_b128 v[148:151], v145
	ds_read_b128 v[152:155], v145 offset:1024
	ds_read_b128 v[156:159], v145 offset:2048
	ds_read_b128 v[160:163], v145 offset:3072
	s_add_u32 s66, s65, 0x80100
	s_addc_u32 s67, s70, 0
	s_mov_b32 m0, s37
	ds_read_b128 v[164:167], v133 offset:32768
	ds_read_b128 v[184:187], v133 offset:33792
	ds_read_b128 v[188:191], v134 offset:32768
	ds_read_b128 v[192:195], v134 offset:33792
	ds_read_b128 v[196:199], v137 offset:32768
	ds_read_b128 v[200:203], v137 offset:33792
	ds_read_b128 v[204:207], v139 offset:32768
	ds_read_b128 v[208:211], v139 offset:33792
	v_lshl_add_u64 v[146:147], s[66:67], 0, v[0:1]
	global_load_lds_dwordx4 v[146:147], off
	v_lshl_add_u64 v[146:147], s[66:67], 0, v[140:141]
	s_mov_b32 m0, s38
	s_nop 0
	global_load_lds_dwordx4 v[146:147], off
	s_waitcnt lgkmcnt(8)
	s_barrier
	s_waitcnt lgkmcnt(0)
	s_waitcnt lgkmcnt(0)
	v_mfma_f32_16x16x32_bf16 v[126:129], v[164:167], v[148:151], v[126:129]
	v_mfma_f32_16x16x32_bf16 v[122:125], v[164:167], v[156:159], v[122:125]
	v_mfma_f32_16x16x32_bf16 v[118:121], v[188:191], v[148:151], v[118:121]
	v_mfma_f32_16x16x32_bf16 v[114:117], v[188:191], v[156:159], v[114:117]
	v_mfma_f32_16x16x32_bf16 v[110:113], v[196:199], v[148:151], v[110:113]
	v_mfma_f32_16x16x32_bf16 v[106:109], v[196:199], v[156:159], v[106:109]
	v_mfma_f32_16x16x32_bf16 v[102:105], v[204:207], v[148:151], v[102:105]
	v_mfma_f32_16x16x32_bf16 v[98:101], v[204:207], v[156:159], v[98:101]
	v_mfma_f32_16x16x32_bf16 v[126:129], v[184:187], v[152:155], v[126:129]
	v_mfma_f32_16x16x32_bf16 v[122:125], v[184:187], v[160:163], v[122:125]
	v_mfma_f32_16x16x32_bf16 v[118:121], v[192:195], v[152:155], v[118:121]
	v_mfma_f32_16x16x32_bf16 v[114:117], v[192:195], v[160:163], v[114:117]
	v_mfma_f32_16x16x32_bf16 v[110:113], v[200:203], v[152:155], v[110:113]
	v_mfma_f32_16x16x32_bf16 v[106:109], v[200:203], v[160:163], v[106:109]
	v_mfma_f32_16x16x32_bf16 v[102:105], v[208:211], v[152:155], v[102:105]
	v_mfma_f32_16x16x32_bf16 v[98:101], v[208:211], v[160:163], v[98:101]
	s_barrier
	s_add_u32 s66, s59, 0x180
	v_add_u32_e32 v146, s78, v142
	s_addc_u32 s67, s63, 0
	s_mov_b32 m0, s39
	ds_read_b128 v[212:215], v146
	ds_read_b128 v[216:219], v146 offset:1024
	ds_read_b128 v[220:223], v146 offset:2048
	ds_read_b128 v[224:227], v146 offset:3072
	v_lshl_add_u64 v[228:229], s[66:67], 0, v[0:1]
	global_load_lds_dwordx4 v[228:229], off
	v_lshl_add_u64 v[228:229], s[66:67], 0, v[140:141]
	s_mov_b32 m0, s40
	s_nop 0
	global_load_lds_dwordx4 v[228:229], off
	s_barrier
	s_waitcnt lgkmcnt(0)
	s_waitcnt lgkmcnt(0)
	v_mfma_f32_16x16x32_bf16 v[94:97], v[164:167], v[212:215], v[94:97]
	v_mfma_f32_16x16x32_bf16 v[90:93], v[164:167], v[220:223], v[90:93]
	v_mfma_f32_16x16x32_bf16 v[86:89], v[188:191], v[212:215], v[86:89]
	v_mfma_f32_16x16x32_bf16 v[82:85], v[188:191], v[220:223], v[82:85]
	v_mfma_f32_16x16x32_bf16 v[78:81], v[196:199], v[212:215], v[78:81]
	v_mfma_f32_16x16x32_bf16 v[74:77], v[196:199], v[220:223], v[74:77]
	v_mfma_f32_16x16x32_bf16 v[70:73], v[204:207], v[212:215], v[70:73]
	v_mfma_f32_16x16x32_bf16 v[66:69], v[204:207], v[220:223], v[66:69]
	v_mfma_f32_16x16x32_bf16 v[94:97], v[184:187], v[216:219], v[94:97]
	v_mfma_f32_16x16x32_bf16 v[90:93], v[184:187], v[224:227], v[90:93]
	v_mfma_f32_16x16x32_bf16 v[86:89], v[192:195], v[216:219], v[86:89]
	v_mfma_f32_16x16x32_bf16 v[82:85], v[192:195], v[224:227], v[82:85]
	v_mfma_f32_16x16x32_bf16 v[78:81], v[200:203], v[216:219], v[78:81]
	v_mfma_f32_16x16x32_bf16 v[74:77], v[200:203], v[224:227], v[74:77]
	v_mfma_f32_16x16x32_bf16 v[70:73], v[208:211], v[216:219], v[70:73]
	v_mfma_f32_16x16x32_bf16 v[66:69], v[208:211], v[224:227], v[66:69]
	s_barrier
	s_add_u32 s66, s65, 0x180
	s_addc_u32 s67, s70, 0
	s_mov_b32 m0, s41
	ds_read_b128 v[164:167], v133 offset:49152
	ds_read_b128 v[184:187], v133 offset:50176
	ds_read_b128 v[188:191], v134 offset:49152
	ds_read_b128 v[192:195], v134 offset:50176
	ds_read_b128 v[196:199], v137 offset:49152
	ds_read_b128 v[200:203], v137 offset:50176
	ds_read_b128 v[204:207], v139 offset:49152
	ds_read_b128 v[208:211], v139 offset:50176
	v_lshl_add_u64 v[228:229], s[66:67], 0, v[0:1]
	global_load_lds_dwordx4 v[228:229], off
	v_lshl_add_u64 v[228:229], s[66:67], 0, v[140:141]
	s_mov_b32 m0, s42
	s_nop 0
	global_load_lds_dwordx4 v[228:229], off
	s_barrier
; #define LDA(dst, b, h) for (int m = 0; m < 4; ++m) for (int k = 0; k < 2; ++k) \
;     dst[m][k] = *reinterpret_cast<const bf16x8*>((char*)SA(b, h) + lds_byte(wr * 64 + m * 16 + fr, k * 32 + fq * 8))
; #define LDB(dst, b, h) for (int n = 0; n < 2; ++n) for (int k = 0; k < 2; ++k) \
;     dst[n][k] = *reinterpret_cast<const bf16x8*>((char*)SB(b, h) + lds_byte(wc * 32 + n * 16 + fr, k * 32 + fq * 8))
; #define MMA(ai, bj, At, Bt_) do { __builtin_amdgcn_s_setprio(1); \
;     for (int m = 0; m < 4; ++m) for (int n = 0; n < 2; ++n) for (int k = 0; k < 2; ++k) \
;       acc[ai][bj][m][n] = __builtin_amdgcn_mfma_f32_16x16x32_bf16(At[m][k], Bt_[n][k], acc[ai][bj][m][n], 0, 0, 0); \
;     __builtin_amdgcn_s_setprio(0); } while (0)
; #define WAIT_V(n) asm volatile("s_waitcnt vmcnt(" #n ")" ::: "memory")
; #define WAIT_L(n) asm volatile("s_waitcnt lgkmcnt(" #n ")" ::: "memory")
; #define BAR __builtin_amdgcn_s_barrier()
; #define SCHED __builtin_amdgcn_sched_barrier(0)
;     ...
;       BAR; WAIT_L(0); MMA(1, 0, At, B0); BAR; SCHED;
;       STAGE(SB(1, 1), Bt, bcol + HALF, t + 3);
;       WAIT_V(6); BAR; MMA(1, 1, At, B1); BAR;
;     }
;     { LDB(B0, 0, 0); LDA(At, 0, 0); STAGE(SA(1, 1), A, brow + HALF, nt - 1);
;       BAR; WAIT_L(0); MMA(0, 0, At, B0); BAR;
;       LDB(B1, 0, 1); BAR; WAIT_L(0); MMA(0, 1, At, B1); BAR;
	s_waitcnt lgkmcnt(0)
	s_waitcnt lgkmcnt(0)
	v_mfma_f32_16x16x32_bf16 v[62:65], v[164:167], v[148:151], v[62:65]
	v_mfma_f32_16x16x32_bf16 v[58:61], v[164:167], v[156:159], v[58:61]
	v_mfma_f32_16x16x32_bf16 v[54:57], v[188:191], v[148:151], v[54:57]
	v_mfma_f32_16x16x32_bf16 v[50:53], v[188:191], v[156:159], v[50:53]
	v_mfma_f32_16x16x32_bf16 v[46:49], v[196:199], v[148:151], v[46:49]
	v_mfma_f32_16x16x32_bf16 v[42:45], v[196:199], v[156:159], v[42:45]
	v_mfma_f32_16x16x32_bf16 v[38:41], v[204:207], v[148:151], v[38:41]
	v_mfma_f32_16x16x32_bf16 v[34:37], v[204:207], v[156:159], v[34:37]
	v_mfma_f32_16x16x32_bf16 v[62:65], v[184:187], v[152:155], v[62:65]
	v_mfma_f32_16x16x32_bf16 v[58:61], v[184:187], v[160:163], v[58:61]
	v_mfma_f32_16x16x32_bf16 v[54:57], v[192:195], v[152:155], v[54:57]
	v_mfma_f32_16x16x32_bf16 v[50:53], v[192:195], v[160:163], v[50:53]
	v_mfma_f32_16x16x32_bf16 v[46:49], v[200:203], v[152:155], v[46:49]
	v_mfma_f32_16x16x32_bf16 v[42:45], v[200:203], v[160:163], v[42:45]
	v_mfma_f32_16x16x32_bf16 v[38:41], v[208:211], v[152:155], v[38:41]
	v_mfma_f32_16x16x32_bf16 v[34:37], v[208:211], v[160:163], v[34:37]
	s_barrier
	s_add_u32 s66, s59, 0x80180
	s_addc_u32 s67, s63, 0
	s_mov_b32 m0, s18
	v_lshl_add_u64 v[148:149], s[66:67], 0, v[0:1]
	global_load_lds_dwordx4 v[148:149], off
	v_lshl_add_u64 v[148:149], s[66:67], 0, v[140:141]
	s_mov_b32 m0, s19
	s_nop 0
	global_load_lds_dwordx4 v[148:149], off
	s_add_u32 s11, s11, 0x100
	s_addc_u32 s44, s44, 0
	s_add_u32 s13, s13, 0x100
	s_addc_u32 s45, s45, 0
	s_add_u32 s50, s50, 0x100
	s_addc_u32 s51, s51, 0
	s_cmp_ge_u32 s55, s43
	s_waitcnt vmcnt(6)
	s_barrier
	v_mfma_f32_16x16x32_bf16 v[30:33], v[164:167], v[212:215], v[30:33]
	v_mfma_f32_16x16x32_bf16 v[26:29], v[164:167], v[220:223], v[26:29]
	v_mfma_f32_16x16x32_bf16 v[22:25], v[188:191], v[212:215], v[22:25]
	v_mfma_f32_16x16x32_bf16 v[18:21], v[188:191], v[220:223], v[18:21]
	v_mfma_f32_16x16x32_bf16 v[14:17], v[196:199], v[212:215], v[14:17]
	v_mfma_f32_16x16x32_bf16 v[10:13], v[196:199], v[220:223], v[10:13]
	v_mfma_f32_16x16x32_bf16 v[6:9], v[204:207], v[212:215], v[6:9]
	v_mfma_f32_16x16x32_bf16 v[2:5], v[204:207], v[220:223], v[2:5]
	v_mfma_f32_16x16x32_bf16 v[30:33], v[184:187], v[216:219], v[30:33]
	v_mfma_f32_16x16x32_bf16 v[26:29], v[184:187], v[224:227], v[26:29]
	v_mfma_f32_16x16x32_bf16 v[22:25], v[192:195], v[216:219], v[22:25]
	v_mfma_f32_16x16x32_bf16 v[18:21], v[192:195], v[224:227], v[18:21]
	v_mfma_f32_16x16x32_bf16 v[14:17], v[200:203], v[216:219], v[14:17]
	v_mfma_f32_16x16x32_bf16 v[10:13], v[200:203], v[224:227], v[10:13]
	v_mfma_f32_16x16x32_bf16 v[6:9], v[208:211], v[216:219], v[6:9]
	v_mfma_f32_16x16x32_bf16 v[2:5], v[208:211], v[224:227], v[2:5]
	s_barrier
	s_cbranch_scc0 .LBB0_202
	s_add_i32 s11, s48, s20
	s_add_i32 s48, s11, -1
	s_lshl_b64 s[16:17], s[48:49], 7
	s_add_u32 s11, s74, s16
	s_addc_u32 s13, s75, s17
	s_add_u32 s4, s11, s4
	s_addc_u32 s5, s13, s5
	s_mov_b32 m0, s58
	ds_read_b128 v[148:151], v143
	ds_read_b128 v[152:155], v143 offset:1024
	ds_read_b128 v[156:159], v143 offset:2048
	ds_read_b128 v[160:163], v143 offset:3072
	ds_read_b128 v[164:167], v133
	ds_read_b128 v[184:187], v133 offset:1024
	ds_read_b128 v[188:191], v134
	ds_read_b128 v[192:195], v134 offset:1024
	ds_read_b128 v[196:199], v137
	ds_read_b128 v[200:203], v137 offset:1024
	ds_read_b128 v[204:207], v139
	ds_read_b128 v[208:211], v139 offset:1024
	s_nop 0
	v_lshl_add_u64 v[142:143], s[4:5], 0, v[0:1]
	global_load_lds_dwordx4 v[142:143], off
	v_lshl_add_u64 v[140:141], s[4:5], 0, v[140:141]
	s_mov_b32 m0, s57
	s_nop 0
	global_load_lds_dwordx4 v[140:141], off
	s_barrier
	s_waitcnt lgkmcnt(0)
	s_setprio 1
	s_waitcnt lgkmcnt(0)
	v_mfma_f32_16x16x32_bf16 v[126:129], v[164:167], v[148:151], v[126:129]
	v_mfma_f32_16x16x32_bf16 v[122:125], v[164:167], v[156:159], v[122:125]
	v_mfma_f32_16x16x32_bf16 v[118:121], v[188:191], v[148:151], v[118:121]
	v_mfma_f32_16x16x32_bf16 v[110:113], v[196:199], v[148:151], v[110:113]
	v_mfma_f32_16x16x32_bf16 v[106:109], v[196:199], v[156:159], v[106:109]
	v_mfma_f32_16x16x32_bf16 v[102:105], v[204:207], v[148:151], v[102:105]
	v_mfma_f32_16x16x32_bf16 v[98:101], v[204:207], v[156:159], v[98:101]
	v_mfma_f32_16x16x32_bf16 v[126:129], v[184:187], v[152:155], v[126:129]
	v_mfma_f32_16x16x32_bf16 v[122:125], v[184:187], v[160:163], v[122:125]
	v_mfma_f32_16x16x32_bf16 v[118:121], v[192:195], v[152:155], v[118:121]
	v_mfma_f32_16x16x32_bf16 v[114:117], v[188:191], v[156:159], v[114:117]
	v_mfma_f32_16x16x32_bf16 v[110:113], v[200:203], v[152:155], v[110:113]
	v_mfma_f32_16x16x32_bf16 v[106:109], v[200:203], v[160:163], v[106:109]
	v_mfma_f32_16x16x32_bf16 v[102:105], v[208:211], v[152:155], v[102:105]
	v_mfma_f32_16x16x32_bf16 v[98:101], v[208:211], v[160:163], v[98:101]
	v_mfma_f32_16x16x32_bf16 v[140:143], v[192:195], v[160:163], v[114:117]
	s_setprio 0
	s_barrier
	s_nop 0
	ds_read_b128 v[114:117], v144
	ds_read_b128 v[212:215], v144 offset:1024
	ds_read_b128 v[216:219], v144 offset:2048
	ds_read_b128 v[220:223], v144 offset:3072
	s_barrier
; #define LDA(dst, b, h) for (int m = 0; m < 4; ++m) for (int k = 0; k < 2; ++k) \
;     dst[m][k] = *reinterpret_cast<const bf16x8*>((char*)SA(b, h) + lds_byte(wr * 64 + m * 16 + fr, k * 32 + fq * 8))
; #define LDB(dst, b, h) for (int n = 0; n < 2; ++n) for (int k = 0; k < 2; ++k) \
;     dst[n][k] = *reinterpret_cast<const bf16x8*>((char*)SB(b, h) + lds_byte(wc * 32 + n * 16 + fr, k * 32 + fq * 8))
; #define MMA(ai, bj, At, Bt_) do { __builtin_amdgcn_s_setprio(1); \
;     for (int m = 0; m < 4; ++m) for (int n = 0; n < 2; ++n) for (int k = 0; k < 2; ++k) \
;       acc[ai][bj][m][n] = __builtin_amdgcn_mfma_f32_16x16x32_bf16(At[m][k], Bt_[n][k], acc[ai][bj][m][n], 0, 0, 0); \
;     __builtin_amdgcn_s_setprio(0); } while (0)
; #define WAIT_V(n) asm volatile("s_waitcnt vmcnt(" #n ")" ::: "memory")
; #define WAIT_L(n) asm volatile("s_waitcnt lgkmcnt(" #n ")" ::: "memory")
; #define BAR __builtin_amdgcn_s_barrier()
;     ...
;       LDB(B1, 0, 1); BAR; WAIT_L(0); MMA(0, 1, At, B1); BAR;
;       LDA(At, 0, 1); WAIT_V(4); BAR; WAIT_L(0); MMA(1, 0, At, B0); MMA(1, 1, At, B1); BAR; }
;     { LDB(B0, 1, 0); LDA(At, 1, 0); WAIT_V(2); BAR; WAIT_L(0); MMA(0, 0, At, B0); BAR;
	s_waitcnt lgkmcnt(0)
	s_setprio 1
	s_waitcnt lgkmcnt(0)
	v_mfma_f32_16x16x32_bf16 v[90:93], v[164:167], v[216:219], v[90:93]
	v_mfma_f32_16x16x32_bf16 v[86:89], v[188:191], v[114:117], v[86:89]
	v_mfma_f32_16x16x32_bf16 v[94:97], v[164:167], v[114:117], v[94:97]
	v_mfma_f32_16x16x32_bf16 v[90:93], v[184:187], v[220:223], v[90:93]
	v_mfma_f32_16x16x32_bf16 v[86:89], v[192:195], v[212:215], v[86:89]
	v_mfma_f32_16x16x32_bf16 v[82:85], v[188:191], v[216:219], v[82:85]
	v_mfma_f32_16x16x32_bf16 v[78:81], v[196:199], v[114:117], v[78:81]
	v_mfma_f32_16x16x32_bf16 v[74:77], v[196:199], v[216:219], v[74:77]
	v_mfma_f32_16x16x32_bf16 v[70:73], v[204:207], v[114:117], v[70:73]
	v_mfma_f32_16x16x32_bf16 v[66:69], v[204:207], v[216:219], v[66:69]
	v_mfma_f32_16x16x32_bf16 v[224:227], v[184:187], v[212:215], v[94:97]
	v_mfma_f32_16x16x32_bf16 v[164:167], v[192:195], v[220:223], v[82:85]
	v_mfma_f32_16x16x32_bf16 v[184:187], v[200:203], v[212:215], v[78:81]
	v_mfma_f32_16x16x32_bf16 v[188:191], v[200:203], v[220:223], v[74:77]
	v_mfma_f32_16x16x32_bf16 v[192:195], v[208:211], v[212:215], v[70:73]
	v_mfma_f32_16x16x32_bf16 v[196:199], v[208:211], v[220:223], v[66:69]
	s_setprio 0
	s_barrier
	s_nop 0
	ds_read_b128 v[66:69], v133 offset:16384
	ds_read_b128 v[70:73], v133 offset:17408
	ds_read_b128 v[74:77], v134 offset:16384
	ds_read_b128 v[78:81], v134 offset:17408
	ds_read_b128 v[82:85], v137 offset:16384
	ds_read_b128 v[94:97], v137 offset:17408
	ds_read_b128 v[200:203], v139 offset:16384
	ds_read_b128 v[204:207], v139 offset:17408
	s_waitcnt vmcnt(4)
	s_barrier
	s_waitcnt lgkmcnt(0)
	s_setprio 1
	s_waitcnt lgkmcnt(0)
	v_mfma_f32_16x16x32_bf16 v[62:65], v[66:69], v[148:151], v[62:65]
	v_mfma_f32_16x16x32_bf16 v[58:61], v[66:69], v[156:159], v[58:61]
	v_mfma_f32_16x16x32_bf16 v[54:57], v[74:77], v[148:151], v[54:57]
	v_mfma_f32_16x16x32_bf16 v[50:53], v[74:77], v[156:159], v[50:53]
	v_mfma_f32_16x16x32_bf16 v[46:49], v[82:85], v[148:151], v[46:49]
	v_mfma_f32_16x16x32_bf16 v[42:45], v[82:85], v[156:159], v[42:45]
	v_mfma_f32_16x16x32_bf16 v[38:41], v[200:203], v[148:151], v[38:41]
	v_mfma_f32_16x16x32_bf16 v[34:37], v[200:203], v[156:159], v[34:37]
	v_mfma_f32_16x16x32_bf16 v[62:65], v[70:73], v[152:155], v[62:65]
	v_mfma_f32_16x16x32_bf16 v[58:61], v[70:73], v[160:163], v[58:61]
	v_mfma_f32_16x16x32_bf16 v[54:57], v[78:81], v[152:155], v[54:57]
	v_mfma_f32_16x16x32_bf16 v[50:53], v[78:81], v[160:163], v[50:53]
	v_mfma_f32_16x16x32_bf16 v[46:49], v[94:97], v[152:155], v[46:49]
	v_mfma_f32_16x16x32_bf16 v[42:45], v[94:97], v[160:163], v[42:45]
	v_mfma_f32_16x16x32_bf16 v[38:41], v[204:207], v[152:155], v[38:41]
	v_mfma_f32_16x16x32_bf16 v[34:37], v[204:207], v[160:163], v[34:37]
	s_setprio 0
	s_setprio 1
	v_mfma_f32_16x16x32_bf16 v[30:33], v[66:69], v[114:117], v[30:33]
	v_mfma_f32_16x16x32_bf16 v[26:29], v[66:69], v[216:219], v[26:29]
	v_mfma_f32_16x16x32_bf16 v[22:25], v[74:77], v[114:117], v[22:25]
	v_mfma_f32_16x16x32_bf16 v[18:21], v[74:77], v[216:219], v[18:21]
	v_mfma_f32_16x16x32_bf16 v[14:17], v[82:85], v[114:117], v[14:17]
	v_mfma_f32_16x16x32_bf16 v[10:13], v[82:85], v[216:219], v[10:13]
	v_mfma_f32_16x16x32_bf16 v[6:9], v[200:203], v[114:117], v[6:9]
	v_mfma_f32_16x16x32_bf16 v[2:5], v[200:203], v[216:219], v[2:5]
	v_mfma_f32_16x16x32_bf16 v[148:151], v[70:73], v[212:215], v[30:33]
	v_mfma_f32_16x16x32_bf16 v[152:155], v[70:73], v[220:223], v[26:29]
	v_mfma_f32_16x16x32_bf16 v[156:159], v[78:81], v[212:215], v[22:25]
	v_mfma_f32_16x16x32_bf16 v[160:163], v[78:81], v[220:223], v[18:21]
	v_mfma_f32_16x16x32_bf16 v[208:211], v[94:97], v[212:215], v[14:17]
	v_mfma_f32_16x16x32_bf16 v[228:231], v[94:97], v[220:223], v[10:13]
	v_mfma_f32_16x16x32_bf16 v[212:215], v[204:207], v[212:215], v[6:9]
	v_mfma_f32_16x16x32_bf16 v[200:203], v[204:207], v[220:223], v[2:5]
	s_setprio 0
	s_barrier
	ds_read_b128 v[14:17], v145
	ds_read_b128 v[30:33], v145 offset:1024
	ds_read_b128 v[204:207], v145 offset:2048
	ds_read_b128 v[216:219], v145 offset:3072
	ds_read_b128 v[2:5], v133 offset:32768
	ds_read_b128 v[6:9], v133 offset:33792
	ds_read_b128 v[10:13], v134 offset:32768
	ds_read_b128 v[18:21], v134 offset:33792
	ds_read_b128 v[22:25], v137 offset:32768
	ds_read_b128 v[26:29], v137 offset:33792
	ds_read_b128 v[220:223], v139 offset:32768
	ds_read_b128 v[232:235], v139 offset:33792
	s_waitcnt vmcnt(2)
	s_barrier
; #define LDA(dst, b, h) for (int m = 0; m < 4; ++m) for (int k = 0; k < 2; ++k) \
;     dst[m][k] = *reinterpret_cast<const bf16x8*>((char*)SA(b, h) + lds_byte(wr * 64 + m * 16 + fr, k * 32 + fq * 8))
; #define LDB(dst, b, h) for (int n = 0; n < 2; ++n) for (int k = 0; k < 2; ++k) \
;     dst[n][k] = *reinterpret_cast<const bf16x8*>((char*)SB(b, h) + lds_byte(wc * 32 + n * 16 + fr, k * 32 + fq * 8))
; #define MMA(ai, bj, At, Bt_) do { __builtin_amdgcn_s_setprio(1); \
;     for (int m = 0; m < 4; ++m) for (int n = 0; n < 2; ++n) for (int k = 0; k < 2; ++k) \
;       acc[ai][bj][m][n] = __builtin_amdgcn_mfma_f32_16x16x32_bf16(At[m][k], Bt_[n][k], acc[ai][bj][m][n], 0, 0, 0); \
;     __builtin_amdgcn_s_setprio(0); } while (0)
; #define WAIT_V(n) asm volatile("s_waitcnt vmcnt(" #n ")" ::: "memory")
; #define WAIT_L(n) asm volatile("s_waitcnt lgkmcnt(" #n ")" ::: "memory")
; #define BAR __builtin_amdgcn_s_barrier()
;     ...
;     { LDB(B0, 1, 0); LDA(At, 1, 0); WAIT_V(2); BAR; WAIT_L(0); MMA(0, 0, At, B0); BAR;
;       LDB(B1, 1, 1); WAIT_V(0); BAR; WAIT_L(0); MMA(0, 1, At, B1); BAR;
;       LDA(At, 1, 1); BAR; WAIT_L(0); MMA(1, 0, At, B0); MMA(1, 1, At, B1); BAR; }
;     if (wr == 0) BAR;
	s_waitcnt lgkmcnt(0)
	s_setprio 1
	s_waitcnt lgkmcnt(0)
	v_mfma_f32_16x16x32_bf16 v[66:69], v[2:5], v[14:17], v[126:129]
	v_mfma_f32_16x16x32_bf16 v[114:117], v[6:9], v[30:33], v[66:69]
	v_mfma_f32_16x16x32_bf16 v[66:69], v[2:5], v[204:207], v[122:125]
	v_mfma_f32_16x16x32_bf16 v[126:129], v[6:9], v[216:219], v[66:69]
	v_mfma_f32_16x16x32_bf16 v[66:69], v[10:13], v[14:17], v[118:121]
	v_mfma_f32_16x16x32_bf16 v[82:85], v[18:21], v[30:33], v[66:69]
	v_mfma_f32_16x16x32_bf16 v[66:69], v[10:13], v[204:207], v[140:143]
	v_mfma_f32_16x16x32_bf16 v[94:97], v[18:21], v[216:219], v[66:69]
	v_mfma_f32_16x16x32_bf16 v[66:69], v[22:25], v[14:17], v[110:113]
	v_mfma_f32_16x16x32_bf16 v[74:77], v[26:29], v[30:33], v[66:69]
	v_mfma_f32_16x16x32_bf16 v[66:69], v[22:25], v[204:207], v[106:109]
	v_mfma_f32_16x16x32_bf16 v[78:81], v[26:29], v[216:219], v[66:69]
	v_mfma_f32_16x16x32_bf16 v[66:69], v[220:223], v[14:17], v[102:105]
	v_mfma_f32_16x16x32_bf16 v[70:73], v[220:223], v[204:207], v[98:101]
	v_mfma_f32_16x16x32_bf16 v[66:69], v[232:235], v[30:33], v[66:69]
	v_mfma_f32_16x16x32_bf16 v[70:73], v[232:235], v[216:219], v[70:73]
	s_setprio 0
	s_barrier
	ds_read_b128 v[140:143], v146
	ds_read_b128 v[236:239], v146 offset:1024
	ds_read_b128 v[240:243], v146 offset:2048
	ds_read_b128 v[144:147], v146 offset:3072
	s_waitcnt vmcnt(0)
	s_barrier
	s_waitcnt lgkmcnt(0)
	s_setprio 1
	s_waitcnt lgkmcnt(0)
	v_mfma_f32_16x16x32_bf16 v[98:101], v[2:5], v[140:143], v[224:227]
	v_mfma_f32_16x16x32_bf16 v[2:5], v[2:5], v[240:243], v[90:93]
	v_mfma_f32_16x16x32_bf16 v[118:121], v[6:9], v[144:147], v[2:5]
	v_mfma_f32_16x16x32_bf16 v[2:5], v[10:13], v[140:143], v[86:89]
	v_mfma_f32_16x16x32_bf16 v[102:105], v[18:21], v[236:239], v[2:5]
	v_mfma_f32_16x16x32_bf16 v[2:5], v[10:13], v[240:243], v[164:167]
	v_mfma_f32_16x16x32_bf16 v[122:125], v[18:21], v[144:147], v[2:5]
	v_mfma_f32_16x16x32_bf16 v[2:5], v[22:25], v[140:143], v[184:187]
	v_mfma_f32_16x16x32_bf16 v[90:93], v[26:29], v[236:239], v[2:5]
	v_mfma_f32_16x16x32_bf16 v[2:5], v[22:25], v[240:243], v[188:191]
	v_mfma_f32_16x16x32_bf16 v[110:113], v[26:29], v[144:147], v[2:5]
	v_mfma_f32_16x16x32_bf16 v[2:5], v[220:223], v[140:143], v[192:195]
	v_mfma_f32_16x16x32_bf16 v[86:89], v[232:235], v[236:239], v[2:5]
	v_mfma_f32_16x16x32_bf16 v[2:5], v[220:223], v[240:243], v[196:199]
	v_mfma_f32_16x16x32_bf16 v[98:101], v[6:9], v[236:239], v[98:101]
	v_mfma_f32_16x16x32_bf16 v[106:109], v[232:235], v[144:147], v[2:5]
	s_setprio 0
	s_barrier
	ds_read_b128 v[164:167], v133 offset:49152
	ds_read_b128 v[184:187], v133 offset:50176
	ds_read_b128 v[188:191], v134 offset:49152
	ds_read_b128 v[192:195], v134 offset:50176
	ds_read_b128 v[196:199], v137 offset:49152
	ds_read_b128 v[220:223], v137 offset:50176
	ds_read_b128 v[224:227], v139 offset:49152
	ds_read_b128 v[232:235], v139 offset:50176
	s_barrier
	s_waitcnt lgkmcnt(0)
	s_setprio 1
	s_waitcnt lgkmcnt(0)
	v_mfma_f32_16x16x32_bf16 v[6:9], v[164:167], v[204:207], v[58:61]
	v_mfma_f32_16x16x32_bf16 v[10:13], v[188:191], v[204:207], v[50:53]
	v_mfma_f32_16x16x32_bf16 v[2:5], v[164:167], v[14:17], v[62:65]
	v_mfma_f32_16x16x32_bf16 v[18:21], v[184:187], v[216:219], v[6:9]
	v_mfma_f32_16x16x32_bf16 v[6:9], v[188:191], v[14:17], v[54:57]
	v_mfma_f32_16x16x32_bf16 v[22:25], v[192:195], v[216:219], v[10:13]
	v_mfma_f32_16x16x32_bf16 v[10:13], v[196:199], v[14:17], v[46:49]
	v_mfma_f32_16x16x32_bf16 v[14:17], v[224:227], v[14:17], v[38:41]
	v_mfma_f32_16x16x32_bf16 v[2:5], v[184:187], v[30:33], v[2:5]
	v_mfma_f32_16x16x32_bf16 v[6:9], v[192:195], v[30:33], v[6:9]
	v_mfma_f32_16x16x32_bf16 v[10:13], v[220:223], v[30:33], v[10:13]
	v_mfma_f32_16x16x32_bf16 v[26:29], v[196:199], v[204:207], v[42:45]
	v_mfma_f32_16x16x32_bf16 v[14:17], v[232:235], v[30:33], v[14:17]
	v_mfma_f32_16x16x32_bf16 v[30:33], v[224:227], v[204:207], v[34:37]
	v_mfma_f32_16x16x32_bf16 v[26:29], v[220:223], v[216:219], v[26:29]
	v_mfma_f32_16x16x32_bf16 v[30:33], v[232:235], v[216:219], v[30:33]
	s_setprio 0
	s_setprio 1
	v_mfma_f32_16x16x32_bf16 v[38:41], v[164:167], v[240:243], v[152:155]
	v_mfma_f32_16x16x32_bf16 v[42:45], v[188:191], v[240:243], v[160:163]
	v_mfma_f32_16x16x32_bf16 v[46:49], v[196:199], v[240:243], v[228:231]
	v_mfma_f32_16x16x32_bf16 v[34:37], v[164:167], v[140:143], v[148:151]
	v_mfma_f32_16x16x32_bf16 v[50:53], v[184:187], v[144:147], v[38:41]
	v_mfma_f32_16x16x32_bf16 v[38:41], v[188:191], v[140:143], v[156:159]
	v_mfma_f32_16x16x32_bf16 v[54:57], v[192:195], v[144:147], v[42:45]
	v_mfma_f32_16x16x32_bf16 v[42:45], v[196:199], v[140:143], v[208:211]
	v_mfma_f32_16x16x32_bf16 v[58:61], v[220:223], v[144:147], v[46:49]
	v_mfma_f32_16x16x32_bf16 v[46:49], v[224:227], v[140:143], v[212:215]
	v_mfma_f32_16x16x32_bf16 v[62:65], v[224:227], v[240:243], v[200:203]
	v_mfma_f32_16x16x32_bf16 v[34:37], v[184:187], v[236:239], v[34:37]
	v_mfma_f32_16x16x32_bf16 v[38:41], v[192:195], v[236:239], v[38:41]
	v_mfma_f32_16x16x32_bf16 v[42:45], v[220:223], v[236:239], v[42:45]
	v_mfma_f32_16x16x32_bf16 v[46:49], v[232:235], v[236:239], v[46:49]
	v_mfma_f32_16x16x32_bf16 v[62:65], v[232:235], v[144:147], v[62:65]
	s_setprio 0
	v_readlane_b32 s4, v245, 33
	v_readlane_b32 s5, v245, 34
	s_and_b64 vcc, exec, s[4:5]
	s_barrier
	s_cbranch_vccz .LBB0_205
	s_barrier

; #define LDA(dst, b, h) for (int m = 0; m < 4; ++m) for (int k = 0; k < 2; ++k) \
;     dst[m][k] = *reinterpret_cast<const bf16x8*>((char*)SA(b, h) + lds_byte(wr * 64 + m * 16 + fr, k * 32 + fq * 8))
; #define LDB(dst, b, h) for (int n = 0; n < 2; ++n) for (int k = 0; k < 2; ++k) \
;     dst[n][k] = *reinterpret_cast<const bf16x8*>((char*)SB(b, h) + lds_byte(wc * 32 + n * 16 + fr, k * 32 + fq * 8))
; #define MMA(ai, bj, At, Bt_) do { __builtin_amdgcn_s_setprio(1); \
;     for (int m = 0; m < 4; ++m) for (int n = 0; n < 2; ++n) for (int k = 0; k < 2; ++k) \
;       acc[ai][bj][m][n] = __builtin_amdgcn_mfma_f32_16x16x32_bf16(At[m][k], Bt_[n][k], acc[ai][bj][m][n], 0, 0, 0); \
;     __builtin_amdgcn_s_setprio(0); } while (0)
; #define WAIT_L(n) asm volatile("s_waitcnt lgkmcnt(" #n ")" ::: "memory")
; #define BAR __builtin_amdgcn_s_barrier()
; #define SCHED __builtin_amdgcn_sched_barrier(0)
;     ...
;       LDB(B0, 0, 0); SCHED; LDA(At, 0, 0); STAGE(SA(1, 1), A, brow + HALF, t + 1);
;       WAIT_L(8); BAR; WAIT_L(0); MMA(0, 0, At, B0); BAR; SCHED;
;       LDB(B1, 0, 1); STAGE(SB(0, 0), Bt, bcol, t + 2);
;       BAR; WAIT_L(0); MMA(0, 1, At, B1); BAR;
;       LDA(At, 0, 1); STAGE(SA(0, 0), A, brow, t + 2);
;       BAR; WAIT_L(0); MMA(1, 0, At, B0); BAR; SCHED;
.LBB0_418:
	v_add_u32_e32 v143, s2, v142
	ds_read_b128 v[146:149], v143
	ds_read_b128 v[150:153], v143 offset:1024
	ds_read_b128 v[154:157], v143 offset:2048
	ds_read_b128 v[158:161], v143 offset:3072
	s_add_u32 s42, s30, s6
	s_addc_u32 s43, s31, s7
	s_add_u32 s44, s42, 0x80080
	s_addc_u32 s45, s43, 0
	s_add_i32 s41, s15, 0xc000
	ds_read_b128 v[162:165], v133
	ds_read_b128 v[184:187], v133 offset:1024
	ds_read_b128 v[188:191], v134
	ds_read_b128 v[192:195], v134 offset:1024
	ds_read_b128 v[196:199], v137
	ds_read_b128 v[200:203], v137 offset:1024
	ds_read_b128 v[204:207], v139
	ds_read_b128 v[208:211], v139 offset:1024
	s_mov_b32 m0, s41
	v_lshl_add_u64 v[144:145], s[44:45], 0, v[0:1]
	s_add_i32 s37, s15, 0xe000
	global_load_lds_dwordx4 v[144:145], off
	v_lshl_add_u64 v[144:145], s[44:45], 0, v[140:141]
	s_mov_b32 m0, s37
	s_nop 0
	global_load_lds_dwordx4 v[144:145], off
	s_waitcnt lgkmcnt(8)
	s_barrier
	s_waitcnt lgkmcnt(0)
	s_waitcnt lgkmcnt(0)
	v_mfma_f32_16x16x32_bf16 v[126:129], v[162:165], v[146:149], v[126:129]
	v_mfma_f32_16x16x32_bf16 v[122:125], v[162:165], v[154:157], v[122:125]
	v_mfma_f32_16x16x32_bf16 v[118:121], v[188:191], v[146:149], v[118:121]
	v_mfma_f32_16x16x32_bf16 v[114:117], v[188:191], v[154:157], v[114:117]
	v_mfma_f32_16x16x32_bf16 v[110:113], v[196:199], v[146:149], v[110:113]
	v_mfma_f32_16x16x32_bf16 v[106:109], v[196:199], v[154:157], v[106:109]
	v_mfma_f32_16x16x32_bf16 v[102:105], v[204:207], v[146:149], v[102:105]
	v_mfma_f32_16x16x32_bf16 v[98:101], v[204:207], v[154:157], v[98:101]
	v_mfma_f32_16x16x32_bf16 v[126:129], v[184:187], v[150:153], v[126:129]
	v_mfma_f32_16x16x32_bf16 v[122:125], v[184:187], v[158:161], v[122:125]
	v_mfma_f32_16x16x32_bf16 v[118:121], v[192:195], v[150:153], v[118:121]
	v_mfma_f32_16x16x32_bf16 v[114:117], v[192:195], v[158:161], v[114:117]
	v_mfma_f32_16x16x32_bf16 v[110:113], v[200:203], v[150:153], v[110:113]
	v_mfma_f32_16x16x32_bf16 v[106:109], v[200:203], v[158:161], v[106:109]
	v_mfma_f32_16x16x32_bf16 v[102:105], v[208:211], v[150:153], v[102:105]
	v_mfma_f32_16x16x32_bf16 v[98:101], v[208:211], v[158:161], v[98:101]
	s_barrier
	s_add_u32 s44, s34, s6
	s_addc_u32 s45, s35, s7
	s_add_u32 s50, s44, 0x100
	v_add_u32_e32 v144, s76, v142
	s_addc_u32 s51, s45, 0
	s_mov_b32 m0, s23
	ds_read_b128 v[212:215], v144
	ds_read_b128 v[216:219], v144 offset:1024
	ds_read_b128 v[220:223], v144 offset:2048
	ds_read_b128 v[224:227], v144 offset:3072
	v_lshl_add_u64 v[166:167], s[50:51], 0, v[0:1]
	global_load_lds_dwordx4 v[166:167], off
	v_lshl_add_u64 v[166:167], s[50:51], 0, v[140:141]
	s_mov_b32 m0, s26
	s_nop 0
	global_load_lds_dwordx4 v[166:167], off
	s_barrier
	s_waitcnt lgkmcnt(0)
	s_waitcnt lgkmcnt(0)
	v_mfma_f32_16x16x32_bf16 v[94:97], v[162:165], v[212:215], v[94:97]
	v_mfma_f32_16x16x32_bf16 v[90:93], v[162:165], v[220:223], v[90:93]
	v_mfma_f32_16x16x32_bf16 v[86:89], v[188:191], v[212:215], v[86:89]
	v_mfma_f32_16x16x32_bf16 v[82:85], v[188:191], v[220:223], v[82:85]
	v_mfma_f32_16x16x32_bf16 v[78:81], v[196:199], v[212:215], v[78:81]
	v_mfma_f32_16x16x32_bf16 v[74:77], v[196:199], v[220:223], v[74:77]
	v_mfma_f32_16x16x32_bf16 v[70:73], v[204:207], v[212:215], v[70:73]
	v_mfma_f32_16x16x32_bf16 v[66:69], v[204:207], v[220:223], v[66:69]
	v_mfma_f32_16x16x32_bf16 v[94:97], v[184:187], v[216:219], v[94:97]
	v_mfma_f32_16x16x32_bf16 v[90:93], v[184:187], v[224:227], v[90:93]
	v_mfma_f32_16x16x32_bf16 v[86:89], v[192:195], v[216:219], v[86:89]
	v_mfma_f32_16x16x32_bf16 v[82:85], v[192:195], v[224:227], v[82:85]
	v_mfma_f32_16x16x32_bf16 v[78:81], v[200:203], v[216:219], v[78:81]
	v_mfma_f32_16x16x32_bf16 v[74:77], v[200:203], v[224:227], v[74:77]
	v_mfma_f32_16x16x32_bf16 v[70:73], v[208:211], v[216:219], v[70:73]
	v_mfma_f32_16x16x32_bf16 v[66:69], v[208:211], v[224:227], v[66:69]
	s_barrier
	s_add_u32 s50, s42, 0x100
	s_addc_u32 s51, s43, 0
	s_mov_b32 m0, s15
	ds_read_b128 v[162:165], v133 offset:16384
	ds_read_b128 v[184:187], v133 offset:17408
	ds_read_b128 v[188:191], v134 offset:16384
	ds_read_b128 v[192:195], v134 offset:17408
	ds_read_b128 v[196:199], v137 offset:16384
	ds_read_b128 v[200:203], v137 offset:17408
	ds_read_b128 v[204:207], v139 offset:16384
	ds_read_b128 v[208:211], v139 offset:17408
	v_lshl_add_u64 v[166:167], s[50:51], 0, v[0:1]
	global_load_lds_dwordx4 v[166:167], off
	v_lshl_add_u64 v[166:167], s[50:51], 0, v[140:141]
	s_mov_b32 m0, s25
	s_nop 0
	global_load_lds_dwordx4 v[166:167], off
	s_barrier
	s_waitcnt lgkmcnt(0)
	s_waitcnt lgkmcnt(0)
	v_mfma_f32_16x16x32_bf16 v[62:65], v[162:165], v[146:149], v[62:65]
	v_mfma_f32_16x16x32_bf16 v[58:61], v[162:165], v[154:157], v[58:61]
	v_mfma_f32_16x16x32_bf16 v[54:57], v[188:191], v[146:149], v[54:57]
	v_mfma_f32_16x16x32_bf16 v[50:53], v[188:191], v[154:157], v[50:53]
	v_mfma_f32_16x16x32_bf16 v[46:49], v[196:199], v[146:149], v[46:49]
	v_mfma_f32_16x16x32_bf16 v[42:45], v[196:199], v[154:157], v[42:45]
	v_mfma_f32_16x16x32_bf16 v[38:41], v[204:207], v[146:149], v[38:41]
	v_mfma_f32_16x16x32_bf16 v[34:37], v[204:207], v[154:157], v[34:37]
	v_mfma_f32_16x16x32_bf16 v[62:65], v[184:187], v[150:153], v[62:65]
	v_mfma_f32_16x16x32_bf16 v[58:61], v[184:187], v[158:161], v[58:61]
	v_mfma_f32_16x16x32_bf16 v[54:57], v[192:195], v[150:153], v[54:57]
	v_mfma_f32_16x16x32_bf16 v[50:53], v[192:195], v[158:161], v[50:53]
	v_mfma_f32_16x16x32_bf16 v[46:49], v[200:203], v[150:153], v[46:49]
	v_mfma_f32_16x16x32_bf16 v[42:45], v[200:203], v[158:161], v[42:45]
	v_mfma_f32_16x16x32_bf16 v[38:41], v[208:211], v[150:153], v[38:41]
	v_mfma_f32_16x16x32_bf16 v[34:37], v[208:211], v[158:161], v[34:37]
	s_barrier
; #define LDA(dst, b, h) for (int m = 0; m < 4; ++m) for (int k = 0; k < 2; ++k) \
;     dst[m][k] = *reinterpret_cast<const bf16x8*>((char*)SA(b, h) + lds_byte(wr * 64 + m * 16 + fr, k * 32 + fq * 8))
; #define LDB(dst, b, h) for (int n = 0; n < 2; ++n) for (int k = 0; k < 2; ++k) \
;     dst[n][k] = *reinterpret_cast<const bf16x8*>((char*)SB(b, h) + lds_byte(wc * 32 + n * 16 + fr, k * 32 + fq * 8))
; #define MMA(ai, bj, At, Bt_) do { __builtin_amdgcn_s_setprio(1); \
;     for (int m = 0; m < 4; ++m) for (int n = 0; n < 2; ++n) for (int k = 0; k < 2; ++k) \
;       acc[ai][bj][m][n] = __builtin_amdgcn_mfma_f32_16x16x32_bf16(At[m][k], Bt_[n][k], acc[ai][bj][m][n], 0, 0, 0); \
;     __builtin_amdgcn_s_setprio(0); } while (0)
; #define WAIT_V(n) asm volatile("s_waitcnt vmcnt(" #n ")" ::: "memory")
; #define WAIT_L(n) asm volatile("s_waitcnt lgkmcnt(" #n ")" ::: "memory")
; #define BAR __builtin_amdgcn_s_barrier()
; #define SCHED __builtin_amdgcn_sched_barrier(0)
;     ...
;       STAGE(SB(0, 1), Bt, bcol + HALF, t + 2);
;       WAIT_V(6); BAR; MMA(1, 1, At, B1); BAR;
;       LDB(B0, 1, 0); SCHED; LDA(At, 1, 0); STAGE(SA(0, 1), A, brow + HALF, t + 2);
;       WAIT_L(8); BAR; WAIT_L(0); MMA(0, 0, At, B0); BAR; SCHED;
;       LDB(B1, 1, 1); STAGE(SB(1, 0), Bt, bcol, t + 3);
;       BAR; WAIT_L(0); MMA(0, 1, At, B1); BAR;
;       LDA(At, 1, 1); STAGE(SA(1, 0), A, brow, t + 3);
	s_add_u32 s50, s44, 0x80100
	s_addc_u32 s51, s45, 0
	s_mov_b32 m0, s27
	v_lshl_add_u64 v[146:147], s[50:51], 0, v[0:1]
	global_load_lds_dwordx4 v[146:147], off
	v_lshl_add_u64 v[146:147], s[50:51], 0, v[140:141]
	s_mov_b32 m0, s28
	s_nop 0
	global_load_lds_dwordx4 v[146:147], off
	s_waitcnt vmcnt(6)
	s_barrier
	v_mfma_f32_16x16x32_bf16 v[30:33], v[162:165], v[212:215], v[30:33]
	v_mfma_f32_16x16x32_bf16 v[26:29], v[162:165], v[220:223], v[26:29]
	v_mfma_f32_16x16x32_bf16 v[22:25], v[188:191], v[212:215], v[22:25]
	v_mfma_f32_16x16x32_bf16 v[18:21], v[188:191], v[220:223], v[18:21]
	v_mfma_f32_16x16x32_bf16 v[14:17], v[196:199], v[212:215], v[14:17]
	v_mfma_f32_16x16x32_bf16 v[10:13], v[196:199], v[220:223], v[10:13]
	v_mfma_f32_16x16x32_bf16 v[6:9], v[204:207], v[212:215], v[6:9]
	v_mfma_f32_16x16x32_bf16 v[2:5], v[204:207], v[220:223], v[2:5]
	v_mfma_f32_16x16x32_bf16 v[30:33], v[184:187], v[216:219], v[30:33]
	v_mfma_f32_16x16x32_bf16 v[26:29], v[184:187], v[224:227], v[26:29]
	v_mfma_f32_16x16x32_bf16 v[22:25], v[192:195], v[216:219], v[22:25]
	v_mfma_f32_16x16x32_bf16 v[18:21], v[192:195], v[224:227], v[18:21]
	v_mfma_f32_16x16x32_bf16 v[14:17], v[200:203], v[216:219], v[14:17]
	v_mfma_f32_16x16x32_bf16 v[10:13], v[200:203], v[224:227], v[10:13]
	v_mfma_f32_16x16x32_bf16 v[6:9], v[208:211], v[216:219], v[6:9]
	v_mfma_f32_16x16x32_bf16 v[2:5], v[208:211], v[224:227], v[2:5]
	s_barrier
	v_add_u32_e32 v145, s77, v142
	ds_read_b128 v[148:151], v145
	ds_read_b128 v[152:155], v145 offset:1024
	ds_read_b128 v[156:159], v145 offset:2048
	ds_read_b128 v[160:163], v145 offset:3072
	s_add_u32 s50, s42, 0x80100
	s_addc_u32 s51, s43, 0
	s_mov_b32 m0, s17
	ds_read_b128 v[164:167], v133 offset:32768
	ds_read_b128 v[184:187], v133 offset:33792
	ds_read_b128 v[188:191], v134 offset:32768
	ds_read_b128 v[192:195], v134 offset:33792
	ds_read_b128 v[196:199], v137 offset:32768
	ds_read_b128 v[200:203], v137 offset:33792
	ds_read_b128 v[204:207], v139 offset:32768
	ds_read_b128 v[208:211], v139 offset:33792
	v_lshl_add_u64 v[146:147], s[50:51], 0, v[0:1]
	global_load_lds_dwordx4 v[146:147], off
	v_lshl_add_u64 v[146:147], s[50:51], 0, v[140:141]
	s_mov_b32 m0, s29
	s_nop 0
	global_load_lds_dwordx4 v[146:147], off
	s_waitcnt lgkmcnt(8)
	s_barrier
	s_waitcnt lgkmcnt(0)
	s_waitcnt lgkmcnt(0)
	v_mfma_f32_16x16x32_bf16 v[126:129], v[164:167], v[148:151], v[126:129]
	v_mfma_f32_16x16x32_bf16 v[122:125], v[164:167], v[156:159], v[122:125]
	v_mfma_f32_16x16x32_bf16 v[118:121], v[188:191], v[148:151], v[118:121]
	v_mfma_f32_16x16x32_bf16 v[114:117], v[188:191], v[156:159], v[114:117]
	v_mfma_f32_16x16x32_bf16 v[110:113], v[196:199], v[148:151], v[110:113]
	v_mfma_f32_16x16x32_bf16 v[106:109], v[196:199], v[156:159], v[106:109]
	v_mfma_f32_16x16x32_bf16 v[102:105], v[204:207], v[148:151], v[102:105]
	v_mfma_f32_16x16x32_bf16 v[98:101], v[204:207], v[156:159], v[98:101]
	v_mfma_f32_16x16x32_bf16 v[126:129], v[184:187], v[152:155], v[126:129]
	v_mfma_f32_16x16x32_bf16 v[122:125], v[184:187], v[160:163], v[122:125]
	v_mfma_f32_16x16x32_bf16 v[118:121], v[192:195], v[152:155], v[118:121]
	v_mfma_f32_16x16x32_bf16 v[114:117], v[192:195], v[160:163], v[114:117]
	v_mfma_f32_16x16x32_bf16 v[110:113], v[200:203], v[152:155], v[110:113]
	v_mfma_f32_16x16x32_bf16 v[106:109], v[200:203], v[160:163], v[106:109]
	v_mfma_f32_16x16x32_bf16 v[102:105], v[208:211], v[152:155], v[102:105]
	v_mfma_f32_16x16x32_bf16 v[98:101], v[208:211], v[160:163], v[98:101]
	s_barrier
	s_add_u32 s50, s44, 0x180
	v_add_u32_e32 v146, s78, v142
	s_addc_u32 s51, s45, 0
	s_mov_b32 m0, s8
	ds_read_b128 v[212:215], v146
	ds_read_b128 v[216:219], v146 offset:1024
	ds_read_b128 v[220:223], v146 offset:2048
	ds_read_b128 v[224:227], v146 offset:3072
	v_lshl_add_u64 v[228:229], s[50:51], 0, v[0:1]
	global_load_lds_dwordx4 v[228:229], off
	v_lshl_add_u64 v[228:229], s[50:51], 0, v[140:141]
	s_mov_b32 m0, s9
	s_nop 0
	global_load_lds_dwordx4 v[228:229], off
	s_barrier
	s_waitcnt lgkmcnt(0)
	s_waitcnt lgkmcnt(0)
	v_mfma_f32_16x16x32_bf16 v[94:97], v[164:167], v[212:215], v[94:97]
	v_mfma_f32_16x16x32_bf16 v[90:93], v[164:167], v[220:223], v[90:93]
	v_mfma_f32_16x16x32_bf16 v[86:89], v[188:191], v[212:215], v[86:89]
	v_mfma_f32_16x16x32_bf16 v[82:85], v[188:191], v[220:223], v[82:85]
	v_mfma_f32_16x16x32_bf16 v[78:81], v[196:199], v[212:215], v[78:81]
	v_mfma_f32_16x16x32_bf16 v[74:77], v[196:199], v[220:223], v[74:77]
	v_mfma_f32_16x16x32_bf16 v[70:73], v[204:207], v[212:215], v[70:73]
	v_mfma_f32_16x16x32_bf16 v[66:69], v[204:207], v[220:223], v[66:69]
	v_mfma_f32_16x16x32_bf16 v[94:97], v[184:187], v[216:219], v[94:97]
	v_mfma_f32_16x16x32_bf16 v[90:93], v[184:187], v[224:227], v[90:93]
	v_mfma_f32_16x16x32_bf16 v[86:89], v[192:195], v[216:219], v[86:89]
	v_mfma_f32_16x16x32_bf16 v[82:85], v[192:195], v[224:227], v[82:85]
	v_mfma_f32_16x16x32_bf16 v[78:81], v[200:203], v[216:219], v[78:81]
	v_mfma_f32_16x16x32_bf16 v[74:77], v[200:203], v[224:227], v[74:77]
	v_mfma_f32_16x16x32_bf16 v[70:73], v[208:211], v[216:219], v[70:73]
	v_mfma_f32_16x16x32_bf16 v[66:69], v[208:211], v[224:227], v[66:69]
	s_barrier
	s_add_u32 s42, s42, 0x180
	s_addc_u32 s43, s43, 0
	s_mov_b32 m0, s18
	ds_read_b128 v[164:167], v133 offset:49152
	ds_read_b128 v[184:187], v133 offset:50176
	ds_read_b128 v[188:191], v134 offset:49152
	ds_read_b128 v[192:195], v134 offset:50176
	ds_read_b128 v[196:199], v137 offset:49152
	ds_read_b128 v[200:203], v137 offset:50176
	ds_read_b128 v[204:207], v139 offset:49152
	ds_read_b128 v[208:211], v139 offset:50176
	v_lshl_add_u64 v[228:229], s[42:43], 0, v[0:1]
	global_load_lds_dwordx4 v[228:229], off
	v_lshl_add_u64 v[228:229], s[42:43], 0, v[140:141]
	s_mov_b32 m0, s19
	s_nop 0
	global_load_lds_dwordx4 v[228:229], off
	s_barrier
; #define LDA(dst, b, h) for (int m = 0; m < 4; ++m) for (int k = 0; k < 2; ++k) \
;     dst[m][k] = *reinterpret_cast<const bf16x8*>((char*)SA(b, h) + lds_byte(wr * 64 + m * 16 + fr, k * 32 + fq * 8))
; #define LDB(dst, b, h) for (int n = 0; n < 2; ++n) for (int k = 0; k < 2; ++k) \
;     dst[n][k] = *reinterpret_cast<const bf16x8*>((char*)SB(b, h) + lds_byte(wc * 32 + n * 16 + fr, k * 32 + fq * 8))
; #define MMA(ai, bj, At, Bt_) do { __builtin_amdgcn_s_setprio(1); \
;     for (int m = 0; m < 4; ++m) for (int n = 0; n < 2; ++n) for (int k = 0; k < 2; ++k) \
;       acc[ai][bj][m][n] = __builtin_amdgcn_mfma_f32_16x16x32_bf16(At[m][k], Bt_[n][k], acc[ai][bj][m][n], 0, 0, 0); \
;     __builtin_amdgcn_s_setprio(0); } while (0)
; #define WAIT_V(n) asm volatile("s_waitcnt vmcnt(" #n ")" ::: "memory")
; #define WAIT_L(n) asm volatile("s_waitcnt lgkmcnt(" #n ")" ::: "memory")
; #define BAR __builtin_amdgcn_s_barrier()
; #define SCHED __builtin_amdgcn_sched_barrier(0)
;     ...
;       BAR; WAIT_L(0); MMA(1, 0, At, B0); BAR; SCHED;
;       STAGE(SB(1, 1), Bt, bcol + HALF, t + 3);
;       WAIT_V(6); BAR; MMA(1, 1, At, B1); BAR;
;     }
;     { LDB(B0, 0, 0); LDA(At, 0, 0); STAGE(SA(1, 1), A, brow + HALF, nt - 1);
;       BAR; WAIT_L(0); MMA(0, 0, At, B0); BAR;
;       LDB(B1, 0, 1); BAR; WAIT_L(0); MMA(0, 1, At, B1); BAR;
	s_waitcnt lgkmcnt(0)
	s_waitcnt lgkmcnt(0)
	v_mfma_f32_16x16x32_bf16 v[62:65], v[164:167], v[148:151], v[62:65]
	v_mfma_f32_16x16x32_bf16 v[58:61], v[164:167], v[156:159], v[58:61]
	v_mfma_f32_16x16x32_bf16 v[54:57], v[188:191], v[148:151], v[54:57]
	v_mfma_f32_16x16x32_bf16 v[50:53], v[188:191], v[156:159], v[50:53]
	v_mfma_f32_16x16x32_bf16 v[46:49], v[196:199], v[148:151], v[46:49]
	v_mfma_f32_16x16x32_bf16 v[42:45], v[196:199], v[156:159], v[42:45]
	v_mfma_f32_16x16x32_bf16 v[38:41], v[204:207], v[148:151], v[38:41]
	v_mfma_f32_16x16x32_bf16 v[34:37], v[204:207], v[156:159], v[34:37]
	v_mfma_f32_16x16x32_bf16 v[62:65], v[184:187], v[152:155], v[62:65]
	v_mfma_f32_16x16x32_bf16 v[58:61], v[184:187], v[160:163], v[58:61]
	v_mfma_f32_16x16x32_bf16 v[54:57], v[192:195], v[152:155], v[54:57]
	v_mfma_f32_16x16x32_bf16 v[50:53], v[192:195], v[160:163], v[50:53]
	v_mfma_f32_16x16x32_bf16 v[46:49], v[200:203], v[152:155], v[46:49]
	v_mfma_f32_16x16x32_bf16 v[42:45], v[200:203], v[160:163], v[42:45]
	v_mfma_f32_16x16x32_bf16 v[38:41], v[208:211], v[152:155], v[38:41]
	v_mfma_f32_16x16x32_bf16 v[34:37], v[208:211], v[160:163], v[34:37]
	s_barrier
	s_add_u32 s42, s44, 0x80180
	s_addc_u32 s43, s45, 0
	s_mov_b32 m0, s20
	v_lshl_add_u64 v[148:149], s[42:43], 0, v[0:1]
	global_load_lds_dwordx4 v[148:149], off
	v_lshl_add_u64 v[148:149], s[42:43], 0, v[140:141]
	s_mov_b32 m0, s21
	s_nop 0
	global_load_lds_dwordx4 v[148:149], off
	s_add_i32 s36, s36, 2
	s_add_u32 s6, s6, 0x100
	s_addc_u32 s7, s7, 0
	s_cmp_gt_u32 s36, 27
	s_waitcnt vmcnt(6)
	s_barrier
	v_mfma_f32_16x16x32_bf16 v[30:33], v[164:167], v[212:215], v[30:33]
	v_mfma_f32_16x16x32_bf16 v[26:29], v[164:167], v[220:223], v[26:29]
	v_mfma_f32_16x16x32_bf16 v[22:25], v[188:191], v[212:215], v[22:25]
	v_mfma_f32_16x16x32_bf16 v[18:21], v[188:191], v[220:223], v[18:21]
	v_mfma_f32_16x16x32_bf16 v[14:17], v[196:199], v[212:215], v[14:17]
	v_mfma_f32_16x16x32_bf16 v[10:13], v[196:199], v[220:223], v[10:13]
	v_mfma_f32_16x16x32_bf16 v[6:9], v[204:207], v[212:215], v[6:9]
	v_mfma_f32_16x16x32_bf16 v[2:5], v[204:207], v[220:223], v[2:5]
	v_mfma_f32_16x16x32_bf16 v[30:33], v[184:187], v[216:219], v[30:33]
	v_mfma_f32_16x16x32_bf16 v[26:29], v[184:187], v[224:227], v[26:29]
	v_mfma_f32_16x16x32_bf16 v[22:25], v[192:195], v[216:219], v[22:25]
	v_mfma_f32_16x16x32_bf16 v[18:21], v[192:195], v[224:227], v[18:21]
	v_mfma_f32_16x16x32_bf16 v[14:17], v[200:203], v[216:219], v[14:17]
	v_mfma_f32_16x16x32_bf16 v[10:13], v[200:203], v[224:227], v[10:13]
	v_mfma_f32_16x16x32_bf16 v[6:9], v[208:211], v[216:219], v[6:9]
	v_mfma_f32_16x16x32_bf16 v[2:5], v[208:211], v[224:227], v[2:5]
	s_barrier
	s_cbranch_scc0 .LBB0_418
	s_add_u32 s4, s4, 0xf80
	s_addc_u32 s5, s5, 0
	s_mov_b32 m0, s41
	ds_read_b128 v[148:151], v143
	ds_read_b128 v[152:155], v143 offset:1024
	ds_read_b128 v[156:159], v143 offset:2048
	ds_read_b128 v[160:163], v143 offset:3072
	ds_read_b128 v[164:167], v133
	ds_read_b128 v[184:187], v133 offset:1024
	ds_read_b128 v[188:191], v134
	ds_read_b128 v[192:195], v134 offset:1024
	ds_read_b128 v[196:199], v137
	ds_read_b128 v[200:203], v137 offset:1024
	ds_read_b128 v[204:207], v139
	ds_read_b128 v[208:211], v139 offset:1024
	s_nop 0
	v_lshl_add_u64 v[142:143], s[4:5], 0, v[0:1]
	global_load_lds_dwordx4 v[142:143], off
	v_lshl_add_u64 v[140:141], s[4:5], 0, v[140:141]
	s_mov_b32 m0, s37
	s_nop 0
	global_load_lds_dwordx4 v[140:141], off
	s_barrier
	s_waitcnt lgkmcnt(0)
	s_setprio 1
	s_waitcnt lgkmcnt(0)
	v_mfma_f32_16x16x32_bf16 v[126:129], v[164:167], v[148:151], v[126:129]
	v_mfma_f32_16x16x32_bf16 v[122:125], v[164:167], v[156:159], v[122:125]
	v_mfma_f32_16x16x32_bf16 v[118:121], v[188:191], v[148:151], v[118:121]
	v_mfma_f32_16x16x32_bf16 v[110:113], v[196:199], v[148:151], v[110:113]
	v_mfma_f32_16x16x32_bf16 v[106:109], v[196:199], v[156:159], v[106:109]
	v_mfma_f32_16x16x32_bf16 v[102:105], v[204:207], v[148:151], v[102:105]
	v_mfma_f32_16x16x32_bf16 v[98:101], v[204:207], v[156:159], v[98:101]
	v_mfma_f32_16x16x32_bf16 v[126:129], v[184:187], v[152:155], v[126:129]
	v_mfma_f32_16x16x32_bf16 v[122:125], v[184:187], v[160:163], v[122:125]
	v_mfma_f32_16x16x32_bf16 v[118:121], v[192:195], v[152:155], v[118:121]
	v_mfma_f32_16x16x32_bf16 v[114:117], v[188:191], v[156:159], v[114:117]
	v_mfma_f32_16x16x32_bf16 v[110:113], v[200:203], v[152:155], v[110:113]
	v_mfma_f32_16x16x32_bf16 v[106:109], v[200:203], v[160:163], v[106:109]
	v_mfma_f32_16x16x32_bf16 v[102:105], v[208:211], v[152:155], v[102:105]
	v_mfma_f32_16x16x32_bf16 v[98:101], v[208:211], v[160:163], v[98:101]
	v_mfma_f32_16x16x32_bf16 v[140:143], v[192:195], v[160:163], v[114:117]
	s_setprio 0
	s_barrier
	s_nop 0
	ds_read_b128 v[114:117], v144
	ds_read_b128 v[212:215], v144 offset:1024
	ds_read_b128 v[216:219], v144 offset:2048
	ds_read_b128 v[220:223], v144 offset:3072
	s_barrier
	s_waitcnt lgkmcnt(0)
	s_setprio 1
	s_waitcnt lgkmcnt(0)
	v_mfma_f32_16x16x32_bf16 v[90:93], v[164:167], v[216:219], v[90:93]
	v_mfma_f32_16x16x32_bf16 v[86:89], v[188:191], v[114:117], v[86:89]
	v_mfma_f32_16x16x32_bf16 v[94:97], v[164:167], v[114:117], v[94:97]
	v_mfma_f32_16x16x32_bf16 v[90:93], v[184:187], v[220:223], v[90:93]
	v_mfma_f32_16x16x32_bf16 v[86:89], v[192:195], v[212:215], v[86:89]
	v_mfma_f32_16x16x32_bf16 v[82:85], v[188:191], v[216:219], v[82:85]
	v_mfma_f32_16x16x32_bf16 v[78:81], v[196:199], v[114:117], v[78:81]
	v_mfma_f32_16x16x32_bf16 v[74:77], v[196:199], v[216:219], v[74:77]
	v_mfma_f32_16x16x32_bf16 v[70:73], v[204:207], v[114:117], v[70:73]
	v_mfma_f32_16x16x32_bf16 v[66:69], v[204:207], v[216:219], v[66:69]
	v_mfma_f32_16x16x32_bf16 v[224:227], v[184:187], v[212:215], v[94:97]
	v_mfma_f32_16x16x32_bf16 v[164:167], v[192:195], v[220:223], v[82:85]
	v_mfma_f32_16x16x32_bf16 v[184:187], v[200:203], v[212:215], v[78:81]
	v_mfma_f32_16x16x32_bf16 v[188:191], v[200:203], v[220:223], v[74:77]
	v_mfma_f32_16x16x32_bf16 v[192:195], v[208:211], v[212:215], v[70:73]
	v_mfma_f32_16x16x32_bf16 v[196:199], v[208:211], v[220:223], v[66:69]
	s_setprio 0
	s_barrier
; #define LDA(dst, b, h) for (int m = 0; m < 4; ++m) for (int k = 0; k < 2; ++k) \
;     dst[m][k] = *reinterpret_cast<const bf16x8*>((char*)SA(b, h) + lds_byte(wr * 64 + m * 16 + fr, k * 32 + fq * 8))
; #define LDB(dst, b, h) for (int n = 0; n < 2; ++n) for (int k = 0; k < 2; ++k) \
;     dst[n][k] = *reinterpret_cast<const bf16x8*>((char*)SB(b, h) + lds_byte(wc * 32 + n * 16 + fr, k * 32 + fq * 8))
; #define MMA(ai, bj, At, Bt_) do { __builtin_amdgcn_s_setprio(1); \
;     for (int m = 0; m < 4; ++m) for (int n = 0; n < 2; ++n) for (int k = 0; k < 2; ++k) \
;       acc[ai][bj][m][n] = __builtin_amdgcn_mfma_f32_16x16x32_bf16(At[m][k], Bt_[n][k], acc[ai][bj][m][n], 0, 0, 0); \
;     __builtin_amdgcn_s_setprio(0); } while (0)
; #define WAIT_V(n) asm volatile("s_waitcnt vmcnt(" #n ")" ::: "memory")
; #define WAIT_L(n) asm volatile("s_waitcnt lgkmcnt(" #n ")" ::: "memory")
; #define BAR __builtin_amdgcn_s_barrier()
;     ...
;       LDA(At, 0, 1); WAIT_V(4); BAR; WAIT_L(0); MMA(1, 0, At, B0); MMA(1, 1, At, B1); BAR; }
;     { LDB(B0, 1, 0); LDA(At, 1, 0); WAIT_V(2); BAR; WAIT_L(0); MMA(0, 0, At, B0); BAR;
	s_nop 0
	ds_read_b128 v[66:69], v133 offset:16384
	ds_read_b128 v[70:73], v133 offset:17408
	ds_read_b128 v[74:77], v134 offset:16384
	ds_read_b128 v[78:81], v134 offset:17408
	ds_read_b128 v[82:85], v137 offset:16384
	ds_read_b128 v[94:97], v137 offset:17408
	ds_read_b128 v[200:203], v139 offset:16384
	ds_read_b128 v[204:207], v139 offset:17408
	s_waitcnt vmcnt(4)
	s_barrier
	s_waitcnt lgkmcnt(0)
	s_setprio 1
	s_waitcnt lgkmcnt(0)
	v_mfma_f32_16x16x32_bf16 v[62:65], v[66:69], v[148:151], v[62:65]
	v_mfma_f32_16x16x32_bf16 v[58:61], v[66:69], v[156:159], v[58:61]
	v_mfma_f32_16x16x32_bf16 v[54:57], v[74:77], v[148:151], v[54:57]
	v_mfma_f32_16x16x32_bf16 v[50:53], v[74:77], v[156:159], v[50:53]
	v_mfma_f32_16x16x32_bf16 v[46:49], v[82:85], v[148:151], v[46:49]
	v_mfma_f32_16x16x32_bf16 v[42:45], v[82:85], v[156:159], v[42:45]
	v_mfma_f32_16x16x32_bf16 v[38:41], v[200:203], v[148:151], v[38:41]
	v_mfma_f32_16x16x32_bf16 v[34:37], v[200:203], v[156:159], v[34:37]
	v_mfma_f32_16x16x32_bf16 v[62:65], v[70:73], v[152:155], v[62:65]
	v_mfma_f32_16x16x32_bf16 v[58:61], v[70:73], v[160:163], v[58:61]
	v_mfma_f32_16x16x32_bf16 v[54:57], v[78:81], v[152:155], v[54:57]
	v_mfma_f32_16x16x32_bf16 v[50:53], v[78:81], v[160:163], v[50:53]
	v_mfma_f32_16x16x32_bf16 v[46:49], v[94:97], v[152:155], v[46:49]
	v_mfma_f32_16x16x32_bf16 v[42:45], v[94:97], v[160:163], v[42:45]
	v_mfma_f32_16x16x32_bf16 v[38:41], v[204:207], v[152:155], v[38:41]
	v_mfma_f32_16x16x32_bf16 v[34:37], v[204:207], v[160:163], v[34:37]
	s_setprio 0
	s_setprio 1
	v_mfma_f32_16x16x32_bf16 v[30:33], v[66:69], v[114:117], v[30:33]
	v_mfma_f32_16x16x32_bf16 v[26:29], v[66:69], v[216:219], v[26:29]
	v_mfma_f32_16x16x32_bf16 v[22:25], v[74:77], v[114:117], v[22:25]
	v_mfma_f32_16x16x32_bf16 v[18:21], v[74:77], v[216:219], v[18:21]
	v_mfma_f32_16x16x32_bf16 v[14:17], v[82:85], v[114:117], v[14:17]
	v_mfma_f32_16x16x32_bf16 v[10:13], v[82:85], v[216:219], v[10:13]
	v_mfma_f32_16x16x32_bf16 v[6:9], v[200:203], v[114:117], v[6:9]
	v_mfma_f32_16x16x32_bf16 v[2:5], v[200:203], v[216:219], v[2:5]
	v_mfma_f32_16x16x32_bf16 v[148:151], v[70:73], v[212:215], v[30:33]
	v_mfma_f32_16x16x32_bf16 v[152:155], v[70:73], v[220:223], v[26:29]
	v_mfma_f32_16x16x32_bf16 v[156:159], v[78:81], v[212:215], v[22:25]
	v_mfma_f32_16x16x32_bf16 v[160:163], v[78:81], v[220:223], v[18:21]
	v_mfma_f32_16x16x32_bf16 v[208:211], v[94:97], v[212:215], v[14:17]
	v_mfma_f32_16x16x32_bf16 v[228:231], v[94:97], v[220:223], v[10:13]
	v_mfma_f32_16x16x32_bf16 v[212:215], v[204:207], v[212:215], v[6:9]
	v_mfma_f32_16x16x32_bf16 v[200:203], v[204:207], v[220:223], v[2:5]
	s_setprio 0
	s_barrier
	ds_read_b128 v[14:17], v145
	ds_read_b128 v[30:33], v145 offset:1024
	ds_read_b128 v[204:207], v145 offset:2048
	ds_read_b128 v[216:219], v145 offset:3072
	ds_read_b128 v[2:5], v133 offset:32768
	ds_read_b128 v[6:9], v133 offset:33792
	ds_read_b128 v[10:13], v134 offset:32768
	ds_read_b128 v[18:21], v134 offset:33792
	ds_read_b128 v[22:25], v137 offset:32768
	ds_read_b128 v[26:29], v137 offset:33792
	ds_read_b128 v[220:223], v139 offset:32768
	ds_read_b128 v[232:235], v139 offset:33792
	s_waitcnt vmcnt(2)
	s_barrier
	s_waitcnt lgkmcnt(0)
	s_setprio 1
	s_waitcnt lgkmcnt(0)
	v_mfma_f32_16x16x32_bf16 v[66:69], v[2:5], v[14:17], v[126:129]
	v_mfma_f32_16x16x32_bf16 v[114:117], v[6:9], v[30:33], v[66:69]
	v_mfma_f32_16x16x32_bf16 v[66:69], v[2:5], v[204:207], v[122:125]
	v_mfma_f32_16x16x32_bf16 v[126:129], v[6:9], v[216:219], v[66:69]
	v_mfma_f32_16x16x32_bf16 v[66:69], v[10:13], v[14:17], v[118:121]
	v_mfma_f32_16x16x32_bf16 v[82:85], v[18:21], v[30:33], v[66:69]
	v_mfma_f32_16x16x32_bf16 v[66:69], v[10:13], v[204:207], v[140:143]
	v_mfma_f32_16x16x32_bf16 v[94:97], v[18:21], v[216:219], v[66:69]
	v_mfma_f32_16x16x32_bf16 v[66:69], v[22:25], v[14:17], v[110:113]
	v_mfma_f32_16x16x32_bf16 v[74:77], v[26:29], v[30:33], v[66:69]
	v_mfma_f32_16x16x32_bf16 v[66:69], v[22:25], v[204:207], v[106:109]
	v_mfma_f32_16x16x32_bf16 v[78:81], v[26:29], v[216:219], v[66:69]
	v_mfma_f32_16x16x32_bf16 v[66:69], v[220:223], v[14:17], v[102:105]
	v_mfma_f32_16x16x32_bf16 v[70:73], v[220:223], v[204:207], v[98:101]
	v_mfma_f32_16x16x32_bf16 v[66:69], v[232:235], v[30:33], v[66:69]
	v_mfma_f32_16x16x32_bf16 v[70:73], v[232:235], v[216:219], v[70:73]
	s_setprio 0
	s_barrier
; #define LDA(dst, b, h) for (int m = 0; m < 4; ++m) for (int k = 0; k < 2; ++k) \
;     dst[m][k] = *reinterpret_cast<const bf16x8*>((char*)SA(b, h) + lds_byte(wr * 64 + m * 16 + fr, k * 32 + fq * 8))
; #define LDB(dst, b, h) for (int n = 0; n < 2; ++n) for (int k = 0; k < 2; ++k) \
;     dst[n][k] = *reinterpret_cast<const bf16x8*>((char*)SB(b, h) + lds_byte(wc * 32 + n * 16 + fr, k * 32 + fq * 8))
; #define MMA(ai, bj, At, Bt_) do { __builtin_amdgcn_s_setprio(1); \
;     for (int m = 0; m < 4; ++m) for (int n = 0; n < 2; ++n) for (int k = 0; k < 2; ++k) \
;       acc[ai][bj][m][n] = __builtin_amdgcn_mfma_f32_16x16x32_bf16(At[m][k], Bt_[n][k], acc[ai][bj][m][n], 0, 0, 0); \
;     __builtin_amdgcn_s_setprio(0); } while (0)
; #define WAIT_V(n) asm volatile("s_waitcnt vmcnt(" #n ")" ::: "memory")
; #define WAIT_L(n) asm volatile("s_waitcnt lgkmcnt(" #n ")" ::: "memory")
; #define BAR __builtin_amdgcn_s_barrier()
;     ...
;     { LDB(B0, 1, 0); LDA(At, 1, 0); WAIT_V(2); BAR; WAIT_L(0); MMA(0, 0, At, B0); BAR;
;       LDB(B1, 1, 1); WAIT_V(0); BAR; WAIT_L(0); MMA(0, 1, At, B1); BAR;
;       LDA(At, 1, 1); BAR; WAIT_L(0); MMA(1, 0, At, B0); MMA(1, 1, At, B1); BAR; }
;     if (wr == 0) BAR;
	ds_read_b128 v[140:143], v146
	ds_read_b128 v[236:239], v146 offset:1024
	ds_read_b128 v[240:243], v146 offset:2048
	ds_read_b128 v[144:147], v146 offset:3072
	s_waitcnt vmcnt(0)
	s_barrier
	s_waitcnt lgkmcnt(0)
	s_setprio 1
	s_waitcnt lgkmcnt(0)
	v_mfma_f32_16x16x32_bf16 v[98:101], v[2:5], v[140:143], v[224:227]
	v_mfma_f32_16x16x32_bf16 v[2:5], v[2:5], v[240:243], v[90:93]
	v_mfma_f32_16x16x32_bf16 v[118:121], v[6:9], v[144:147], v[2:5]
	v_mfma_f32_16x16x32_bf16 v[2:5], v[10:13], v[140:143], v[86:89]
	v_mfma_f32_16x16x32_bf16 v[102:105], v[18:21], v[236:239], v[2:5]
	v_mfma_f32_16x16x32_bf16 v[2:5], v[10:13], v[240:243], v[164:167]
	v_mfma_f32_16x16x32_bf16 v[122:125], v[18:21], v[144:147], v[2:5]
	v_mfma_f32_16x16x32_bf16 v[2:5], v[22:25], v[140:143], v[184:187]
	v_mfma_f32_16x16x32_bf16 v[90:93], v[26:29], v[236:239], v[2:5]
	v_mfma_f32_16x16x32_bf16 v[2:5], v[22:25], v[240:243], v[188:191]
	v_mfma_f32_16x16x32_bf16 v[110:113], v[26:29], v[144:147], v[2:5]
	v_mfma_f32_16x16x32_bf16 v[2:5], v[220:223], v[140:143], v[192:195]
	v_mfma_f32_16x16x32_bf16 v[86:89], v[232:235], v[236:239], v[2:5]
	v_mfma_f32_16x16x32_bf16 v[2:5], v[220:223], v[240:243], v[196:199]
	v_mfma_f32_16x16x32_bf16 v[98:101], v[6:9], v[236:239], v[98:101]
	v_mfma_f32_16x16x32_bf16 v[106:109], v[232:235], v[144:147], v[2:5]
	s_setprio 0
	s_barrier
	ds_read_b128 v[164:167], v133 offset:49152
	ds_read_b128 v[184:187], v133 offset:50176
	ds_read_b128 v[188:191], v134 offset:49152
	ds_read_b128 v[192:195], v134 offset:50176
	ds_read_b128 v[196:199], v137 offset:49152
	ds_read_b128 v[220:223], v137 offset:50176
	ds_read_b128 v[224:227], v139 offset:49152
	ds_read_b128 v[232:235], v139 offset:50176
	s_barrier
	s_waitcnt lgkmcnt(0)
	s_setprio 1
	s_waitcnt lgkmcnt(0)
	v_mfma_f32_16x16x32_bf16 v[6:9], v[164:167], v[204:207], v[58:61]
	v_mfma_f32_16x16x32_bf16 v[10:13], v[188:191], v[204:207], v[50:53]
	v_mfma_f32_16x16x32_bf16 v[2:5], v[164:167], v[14:17], v[62:65]
	v_mfma_f32_16x16x32_bf16 v[18:21], v[184:187], v[216:219], v[6:9]
	v_mfma_f32_16x16x32_bf16 v[6:9], v[188:191], v[14:17], v[54:57]
	v_mfma_f32_16x16x32_bf16 v[22:25], v[192:195], v[216:219], v[10:13]
	v_mfma_f32_16x16x32_bf16 v[10:13], v[196:199], v[14:17], v[46:49]
	v_mfma_f32_16x16x32_bf16 v[14:17], v[224:227], v[14:17], v[38:41]
	v_mfma_f32_16x16x32_bf16 v[2:5], v[184:187], v[30:33], v[2:5]
	v_mfma_f32_16x16x32_bf16 v[6:9], v[192:195], v[30:33], v[6:9]
	v_mfma_f32_16x16x32_bf16 v[10:13], v[220:223], v[30:33], v[10:13]
	v_mfma_f32_16x16x32_bf16 v[26:29], v[196:199], v[204:207], v[42:45]
	v_mfma_f32_16x16x32_bf16 v[14:17], v[232:235], v[30:33], v[14:17]
	v_mfma_f32_16x16x32_bf16 v[30:33], v[224:227], v[204:207], v[34:37]
	v_mfma_f32_16x16x32_bf16 v[26:29], v[220:223], v[216:219], v[26:29]
	v_mfma_f32_16x16x32_bf16 v[30:33], v[232:235], v[216:219], v[30:33]
	s_setprio 0
	s_setprio 1
	v_mfma_f32_16x16x32_bf16 v[38:41], v[164:167], v[240:243], v[152:155]
	v_mfma_f32_16x16x32_bf16 v[42:45], v[188:191], v[240:243], v[160:163]
	v_mfma_f32_16x16x32_bf16 v[46:49], v[196:199], v[240:243], v[228:231]
	v_mfma_f32_16x16x32_bf16 v[34:37], v[164:167], v[140:143], v[148:151]
	v_mfma_f32_16x16x32_bf16 v[50:53], v[184:187], v[144:147], v[38:41]
	v_mfma_f32_16x16x32_bf16 v[38:41], v[188:191], v[140:143], v[156:159]
	v_mfma_f32_16x16x32_bf16 v[54:57], v[192:195], v[144:147], v[42:45]
	v_mfma_f32_16x16x32_bf16 v[42:45], v[196:199], v[140:143], v[208:211]
	v_mfma_f32_16x16x32_bf16 v[58:61], v[220:223], v[144:147], v[46:49]
	v_mfma_f32_16x16x32_bf16 v[46:49], v[224:227], v[140:143], v[212:215]
	v_mfma_f32_16x16x32_bf16 v[62:65], v[224:227], v[240:243], v[200:203]
	v_mfma_f32_16x16x32_bf16 v[34:37], v[184:187], v[236:239], v[34:37]
	v_mfma_f32_16x16x32_bf16 v[38:41], v[192:195], v[236:239], v[38:41]
	v_mfma_f32_16x16x32_bf16 v[42:45], v[220:223], v[236:239], v[42:45]
	v_mfma_f32_16x16x32_bf16 v[46:49], v[232:235], v[236:239], v[46:49]
	v_mfma_f32_16x16x32_bf16 v[62:65], v[232:235], v[144:147], v[62:65]
	s_setprio 0
	v_readlane_b32 s4, v245, 33
	v_readlane_b32 s5, v245, 34
	s_and_b64 vcc, exec, s[4:5]
	s_barrier
	s_cbranch_vccz .LBB0_421
	s_barrier
